# GEMM K-loops: last iteration peeled, its 14 dead LDS-DMA re-stage loads dropped and waits recounted
# speedup vs baseline: 1.0069x; 1.0069x over previous
.LBB0_24:
	ds_read_b128 v[154:157], v138
	ds_read_b128 v[158:161], v139
	ds_read_b128 v[162:165], v140
	ds_read_b128 v[194:197], v141
	ds_read_b128 v[198:201], v142
	ds_read_b128 v[202:205], v143
	ds_read_b128 v[206:209], v144
	ds_read_b128 v[210:213], v145
	s_add_u32 s14, s96, s88
	s_addc_u32 s15, s97, s89
	s_add_u32 s14, s14, 0x4000900
	s_addc_u32 s15, s15, 0
	s_add_u32 s36, s42, s88
	s_addc_u32 s37, s43, s89
	s_cmpk_eq_i32 s88, 0x700
	s_cselect_b32 s27, s87, s15
	s_cselect_b32 s26, s86, s14
	s_cselect_b32 s15, s85, s37
	s_cselect_b32 s14, s84, s36
	v_lshl_add_u64 v[166:167], v[130:131], 0, s[88:89]
	s_add_i32 m0, s94, 0xc000
	ds_read_b128 v[214:217], v137
	ds_read_b128 v[218:221], v137 offset:1024
	ds_read_b128 v[222:225], v137 offset:2048
	ds_read_b128 v[226:229], v137 offset:3072
	ds_read_b128 v[230:233], v137 offset:4096
	ds_read_b128 v[234:237], v137 offset:5120
	ds_read_b128 v[238:241], v137 offset:6144
	ds_read_b128 v[242:245], v137 offset:7168
	global_load_lds_dwordx4 v[166:167], off
	v_lshl_add_u64 v[166:167], v[132:133], 0, s[88:89]
	s_mov_b32 m0, s48
	s_nop 0
	global_load_lds_dwordx4 v[166:167], off
	s_waitcnt vmcnt(8)
	s_waitcnt lgkmcnt(0)
	s_barrier
	s_setprio 1
	s_waitcnt lgkmcnt(0)
	v_mfma_f32_16x16x32_bf16 v[124:127], v[154:157], v[214:217], v[124:127]
	v_mfma_f32_16x16x32_bf16 v[120:123], v[162:165], v[214:217], v[120:123]
	v_mfma_f32_16x16x32_bf16 v[116:119], v[154:157], v[222:225], v[116:119]
	v_mfma_f32_16x16x32_bf16 v[112:115], v[162:165], v[222:225], v[112:115]
	v_mfma_f32_16x16x32_bf16 v[108:111], v[154:157], v[230:233], v[108:111]
	v_mfma_f32_16x16x32_bf16 v[104:107], v[162:165], v[230:233], v[104:107]
	v_mfma_f32_16x16x32_bf16 v[76:79], v[154:157], v[238:241], v[76:79]
	v_mfma_f32_16x16x32_bf16 v[72:75], v[162:165], v[238:241], v[72:75]
	v_mfma_f32_16x16x32_bf16 v[124:127], v[158:161], v[218:221], v[124:127]
	v_mfma_f32_16x16x32_bf16 v[120:123], v[194:197], v[218:221], v[120:123]
	v_mfma_f32_16x16x32_bf16 v[116:119], v[158:161], v[226:229], v[116:119]
	v_mfma_f32_16x16x32_bf16 v[112:115], v[194:197], v[226:229], v[112:115]
	v_mfma_f32_16x16x32_bf16 v[108:111], v[158:161], v[234:237], v[108:111]
	v_mfma_f32_16x16x32_bf16 v[104:107], v[194:197], v[234:237], v[104:107]
	v_mfma_f32_16x16x32_bf16 v[76:79], v[158:161], v[242:245], v[76:79]
	v_mfma_f32_16x16x32_bf16 v[72:75], v[194:197], v[242:245], v[72:75]
	s_setprio 0
	s_setprio 1
	v_mfma_f32_16x16x32_bf16 v[100:103], v[198:201], v[214:217], v[100:103]
	v_mfma_f32_16x16x32_bf16 v[96:99], v[206:209], v[214:217], v[96:99]
	v_mfma_f32_16x16x32_bf16 v[92:95], v[198:201], v[222:225], v[92:95]
	v_mfma_f32_16x16x32_bf16 v[88:91], v[206:209], v[222:225], v[88:91]
	v_mfma_f32_16x16x32_bf16 v[84:87], v[198:201], v[230:233], v[84:87]
	v_mfma_f32_16x16x32_bf16 v[80:83], v[206:209], v[230:233], v[80:83]
	v_mfma_f32_16x16x32_bf16 v[52:55], v[198:201], v[238:241], v[52:55]
	v_mfma_f32_16x16x32_bf16 v[44:47], v[206:209], v[238:241], v[44:47]
	v_mfma_f32_16x16x32_bf16 v[100:103], v[202:205], v[218:221], v[100:103]
	v_mfma_f32_16x16x32_bf16 v[96:99], v[210:213], v[218:221], v[96:99]
	v_mfma_f32_16x16x32_bf16 v[92:95], v[202:205], v[226:229], v[92:95]
	v_mfma_f32_16x16x32_bf16 v[88:91], v[210:213], v[226:229], v[88:91]
	v_mfma_f32_16x16x32_bf16 v[84:87], v[202:205], v[234:237], v[84:87]
	v_mfma_f32_16x16x32_bf16 v[80:83], v[210:213], v[234:237], v[80:83]
	v_mfma_f32_16x16x32_bf16 v[52:55], v[202:205], v[242:245], v[52:55]
	v_mfma_f32_16x16x32_bf16 v[44:47], v[210:213], v[242:245], v[44:47]
	s_setprio 0
	s_barrier
	s_mov_b32 m0, s41
	v_lshl_add_u64 v[166:167], s[14:15], 0, v[168:169]
	s_add_u32 s36, s14, 0x40000
	ds_read_b128 v[214:217], v137 offset:16384
	ds_read_b128 v[218:221], v137 offset:17408
	ds_read_b128 v[222:225], v137 offset:18432
	ds_read_b128 v[226:229], v137 offset:19456
	ds_read_b128 v[230:233], v137 offset:20480
	ds_read_b128 v[234:237], v137 offset:21504
	ds_read_b128 v[238:241], v137 offset:22528
	ds_read_b128 v[242:245], v137 offset:23552
	global_load_lds_dwordx4 v[166:167], off
	v_lshl_add_u64 v[246:247], s[14:15], 0, v[128:129]
	s_mov_b32 m0, s59
	s_addc_u32 s37, s15, 0
	global_load_lds_dwordx4 v[246:247], off
	v_lshl_add_u64 v[248:249], s[36:37], 0, v[168:169]
	s_mov_b32 m0, s95
	v_lshl_add_u64 v[250:251], s[26:27], 0, v[128:129]
	global_load_lds_dwordx4 v[248:249], off
	v_lshl_add_u64 v[248:249], s[36:37], 0, v[128:129]
	s_mov_b32 m0, vcc_lo
	s_nop 0
	global_load_lds_dwordx4 v[248:249], off
	v_lshl_add_u64 v[248:249], s[26:27], 0, v[168:169]
	s_mov_b32 m0, s94
	s_nop 0
	global_load_lds_dwordx4 v[248:249], off
	s_mov_b32 m0, vcc_hi
	s_nop 0
	global_load_lds_dwordx4 v[250:251], off
	s_waitcnt vmcnt(8)
	s_waitcnt lgkmcnt(0)
	s_barrier
	s_setprio 1
	s_waitcnt lgkmcnt(0)
	v_mfma_f32_16x16x32_bf16 v[68:71], v[154:157], v[214:217], v[68:71]
	v_mfma_f32_16x16x32_bf16 v[64:67], v[162:165], v[214:217], v[64:67]
	v_mfma_f32_16x16x32_bf16 v[60:63], v[154:157], v[222:225], v[60:63]
	v_mfma_f32_16x16x32_bf16 v[56:59], v[162:165], v[222:225], v[56:59]
	v_mfma_f32_16x16x32_bf16 v[48:51], v[154:157], v[230:233], v[48:51]
	v_mfma_f32_16x16x32_bf16 v[40:43], v[162:165], v[230:233], v[40:43]
	v_mfma_f32_16x16x32_bf16 v[36:39], v[154:157], v[238:241], v[36:39]
	v_mfma_f32_16x16x32_bf16 v[32:35], v[162:165], v[238:241], v[32:35]
	v_mfma_f32_16x16x32_bf16 v[68:71], v[158:161], v[218:221], v[68:71]
	v_mfma_f32_16x16x32_bf16 v[64:67], v[194:197], v[218:221], v[64:67]
	v_mfma_f32_16x16x32_bf16 v[60:63], v[158:161], v[226:229], v[60:63]
	v_mfma_f32_16x16x32_bf16 v[56:59], v[194:197], v[226:229], v[56:59]
	v_mfma_f32_16x16x32_bf16 v[48:51], v[158:161], v[234:237], v[48:51]
	v_mfma_f32_16x16x32_bf16 v[40:43], v[194:197], v[234:237], v[40:43]
	v_mfma_f32_16x16x32_bf16 v[36:39], v[158:161], v[242:245], v[36:39]
	v_mfma_f32_16x16x32_bf16 v[32:35], v[194:197], v[242:245], v[32:35]
	s_setprio 0
	s_setprio 1
	v_mfma_f32_16x16x32_bf16 v[28:31], v[198:201], v[214:217], v[28:31]
	v_mfma_f32_16x16x32_bf16 v[24:27], v[206:209], v[214:217], v[24:27]
	v_mfma_f32_16x16x32_bf16 v[20:23], v[198:201], v[222:225], v[20:23]
	v_mfma_f32_16x16x32_bf16 v[16:19], v[206:209], v[222:225], v[16:19]
	v_mfma_f32_16x16x32_bf16 v[12:15], v[198:201], v[230:233], v[12:15]
	v_mfma_f32_16x16x32_bf16 v[8:11], v[206:209], v[230:233], v[8:11]
	v_mfma_f32_16x16x32_bf16 v[4:7], v[198:201], v[238:241], v[4:7]
	v_mfma_f32_16x16x32_bf16 v[0:3], v[206:209], v[238:241], v[0:3]
	v_mfma_f32_16x16x32_bf16 v[28:31], v[202:205], v[218:221], v[28:31]
	v_mfma_f32_16x16x32_bf16 v[24:27], v[210:213], v[218:221], v[24:27]
	v_mfma_f32_16x16x32_bf16 v[20:23], v[202:205], v[226:229], v[20:23]
	v_mfma_f32_16x16x32_bf16 v[16:19], v[210:213], v[226:229], v[16:19]
	v_mfma_f32_16x16x32_bf16 v[12:15], v[202:205], v[234:237], v[12:15]
	v_mfma_f32_16x16x32_bf16 v[8:11], v[210:213], v[234:237], v[8:11]
	v_mfma_f32_16x16x32_bf16 v[4:7], v[202:205], v[242:245], v[4:7]
	v_mfma_f32_16x16x32_bf16 v[0:3], v[210:213], v[242:245], v[0:3]
	s_setprio 0
	s_barrier
	ds_read_b128 v[154:157], v146
	ds_read_b128 v[158:161], v147
	ds_read_b128 v[162:165], v148
	ds_read_b128 v[194:197], v149
	ds_read_b128 v[198:201], v150
	ds_read_b128 v[202:205], v151
	ds_read_b128 v[206:209], v152
	ds_read_b128 v[210:213], v153
	s_add_u32 s26, s26, 0x40000
	s_addc_u32 s27, s27, 0
	s_mov_b32 m0, s28
	v_lshl_add_u64 v[180:181], s[26:27], 0, v[168:169]
	ds_read_b128 v[214:217], v137 offset:32768
	ds_read_b128 v[218:221], v137 offset:33792
	ds_read_b128 v[222:225], v137 offset:34816
	ds_read_b128 v[226:229], v137 offset:35840
	ds_read_b128 v[230:233], v137 offset:36864
	ds_read_b128 v[234:237], v137 offset:37888
	ds_read_b128 v[238:241], v137 offset:38912
	ds_read_b128 v[242:245], v137 offset:39936
	global_load_lds_dwordx4 v[180:181], off
	v_lshl_add_u64 v[180:181], s[26:27], 0, v[128:129]
	s_mov_b32 m0, s29
	s_nop 0
	global_load_lds_dwordx4 v[180:181], off
	s_waitcnt vmcnt(8)
	s_waitcnt lgkmcnt(0)
	s_barrier
	s_setprio 1
	s_waitcnt lgkmcnt(0)
	v_mfma_f32_16x16x32_bf16 v[124:127], v[154:157], v[214:217], v[124:127]
	v_mfma_f32_16x16x32_bf16 v[120:123], v[162:165], v[214:217], v[120:123]
	v_mfma_f32_16x16x32_bf16 v[116:119], v[154:157], v[222:225], v[116:119]
	v_mfma_f32_16x16x32_bf16 v[112:115], v[162:165], v[222:225], v[112:115]
	v_mfma_f32_16x16x32_bf16 v[108:111], v[154:157], v[230:233], v[108:111]
	v_mfma_f32_16x16x32_bf16 v[104:107], v[162:165], v[230:233], v[104:107]
	v_mfma_f32_16x16x32_bf16 v[76:79], v[154:157], v[238:241], v[76:79]
	v_mfma_f32_16x16x32_bf16 v[72:75], v[162:165], v[238:241], v[72:75]
	v_mfma_f32_16x16x32_bf16 v[124:127], v[158:161], v[218:221], v[124:127]
	v_mfma_f32_16x16x32_bf16 v[120:123], v[194:197], v[218:221], v[120:123]
	v_mfma_f32_16x16x32_bf16 v[116:119], v[158:161], v[226:229], v[116:119]
	v_mfma_f32_16x16x32_bf16 v[112:115], v[194:197], v[226:229], v[112:115]
	v_mfma_f32_16x16x32_bf16 v[108:111], v[158:161], v[234:237], v[108:111]
	v_mfma_f32_16x16x32_bf16 v[104:107], v[194:197], v[234:237], v[104:107]
	v_mfma_f32_16x16x32_bf16 v[76:79], v[158:161], v[242:245], v[76:79]
	v_mfma_f32_16x16x32_bf16 v[72:75], v[194:197], v[242:245], v[72:75]
	s_setprio 0
	s_setprio 1
	v_mfma_f32_16x16x32_bf16 v[100:103], v[198:201], v[214:217], v[100:103]
	v_mfma_f32_16x16x32_bf16 v[96:99], v[206:209], v[214:217], v[96:99]
	v_mfma_f32_16x16x32_bf16 v[92:95], v[198:201], v[222:225], v[92:95]
	v_mfma_f32_16x16x32_bf16 v[88:91], v[206:209], v[222:225], v[88:91]
	v_mfma_f32_16x16x32_bf16 v[84:87], v[198:201], v[230:233], v[84:87]
	v_mfma_f32_16x16x32_bf16 v[80:83], v[206:209], v[230:233], v[80:83]
	v_mfma_f32_16x16x32_bf16 v[52:55], v[198:201], v[238:241], v[52:55]
	v_mfma_f32_16x16x32_bf16 v[44:47], v[206:209], v[238:241], v[44:47]
	v_mfma_f32_16x16x32_bf16 v[100:103], v[202:205], v[218:221], v[100:103]
	v_mfma_f32_16x16x32_bf16 v[96:99], v[210:213], v[218:221], v[96:99]
	v_mfma_f32_16x16x32_bf16 v[92:95], v[202:205], v[226:229], v[92:95]
	v_mfma_f32_16x16x32_bf16 v[88:91], v[210:213], v[226:229], v[88:91]
	v_mfma_f32_16x16x32_bf16 v[84:87], v[202:205], v[234:237], v[84:87]
	v_mfma_f32_16x16x32_bf16 v[80:83], v[210:213], v[234:237], v[80:83]
	v_mfma_f32_16x16x32_bf16 v[52:55], v[202:205], v[242:245], v[52:55]
	v_mfma_f32_16x16x32_bf16 v[44:47], v[210:213], v[242:245], v[44:47]
	s_setprio 0
	s_barrier
	s_mov_b32 m0, s19
	v_lshl_add_u64 v[166:167], v[166:167], 0, s[34:35]
	s_add_u32 s14, s14, 0x40080
	ds_read_b128 v[214:217], v137 offset:49152
	ds_read_b128 v[218:221], v137 offset:50176
	ds_read_b128 v[222:225], v137 offset:51200
	ds_read_b128 v[226:229], v137 offset:52224
	ds_read_b128 v[230:233], v137 offset:53248
	ds_read_b128 v[234:237], v137 offset:54272
	ds_read_b128 v[238:241], v137 offset:55296
	ds_read_b128 v[242:245], v137 offset:56320
	global_load_lds_dwordx4 v[166:167], off
	v_lshl_add_u64 v[166:167], v[246:247], 0, s[34:35]
	s_mov_b32 m0, s30
	s_addc_u32 s15, s15, 0
	global_load_lds_dwordx4 v[166:167], off
	v_lshl_add_u64 v[166:167], s[14:15], 0, v[168:169]
	s_mov_b32 m0, s63
	s_nop 0
	global_load_lds_dwordx4 v[166:167], off
	v_lshl_add_u64 v[166:167], s[14:15], 0, v[128:129]
	s_mov_b32 m0, s24
	s_nop 0
	global_load_lds_dwordx4 v[166:167], off
	v_lshl_add_u64 v[166:167], v[248:249], 0, s[34:35]
	s_mov_b32 m0, s61
	s_nop 0
	global_load_lds_dwordx4 v[166:167], off
	v_lshl_add_u64 v[166:167], v[250:251], 0, s[34:35]
	s_mov_b32 m0, s62
	s_nop 0
	global_load_lds_dwordx4 v[166:167], off
	s_waitcnt vmcnt(8)
	s_waitcnt lgkmcnt(0)
	s_barrier
	s_setprio 1
	s_waitcnt lgkmcnt(0)
	v_mfma_f32_16x16x32_bf16 v[68:71], v[154:157], v[214:217], v[68:71]
	v_mfma_f32_16x16x32_bf16 v[64:67], v[162:165], v[214:217], v[64:67]
	v_mfma_f32_16x16x32_bf16 v[60:63], v[154:157], v[222:225], v[60:63]
	v_mfma_f32_16x16x32_bf16 v[56:59], v[162:165], v[222:225], v[56:59]
	v_mfma_f32_16x16x32_bf16 v[48:51], v[154:157], v[230:233], v[48:51]
	v_mfma_f32_16x16x32_bf16 v[40:43], v[162:165], v[230:233], v[40:43]
	v_mfma_f32_16x16x32_bf16 v[36:39], v[154:157], v[238:241], v[36:39]
	v_mfma_f32_16x16x32_bf16 v[32:35], v[162:165], v[238:241], v[32:35]
	v_mfma_f32_16x16x32_bf16 v[68:71], v[158:161], v[218:221], v[68:71]
	v_mfma_f32_16x16x32_bf16 v[64:67], v[194:197], v[218:221], v[64:67]
	v_mfma_f32_16x16x32_bf16 v[60:63], v[158:161], v[226:229], v[60:63]
	v_mfma_f32_16x16x32_bf16 v[56:59], v[194:197], v[226:229], v[56:59]
	v_mfma_f32_16x16x32_bf16 v[48:51], v[158:161], v[234:237], v[48:51]
	v_mfma_f32_16x16x32_bf16 v[40:43], v[194:197], v[234:237], v[40:43]
	v_mfma_f32_16x16x32_bf16 v[36:39], v[158:161], v[242:245], v[36:39]
	v_mfma_f32_16x16x32_bf16 v[32:35], v[194:197], v[242:245], v[32:35]
	s_setprio 0
	s_setprio 1
	v_mfma_f32_16x16x32_bf16 v[28:31], v[198:201], v[214:217], v[28:31]
	v_mfma_f32_16x16x32_bf16 v[24:27], v[206:209], v[214:217], v[24:27]
	v_mfma_f32_16x16x32_bf16 v[20:23], v[198:201], v[222:225], v[20:23]
	v_mfma_f32_16x16x32_bf16 v[16:19], v[206:209], v[222:225], v[16:19]
	v_mfma_f32_16x16x32_bf16 v[12:15], v[198:201], v[230:233], v[12:15]
	v_mfma_f32_16x16x32_bf16 v[8:11], v[206:209], v[230:233], v[8:11]
	v_mfma_f32_16x16x32_bf16 v[4:7], v[198:201], v[238:241], v[4:7]
	v_mfma_f32_16x16x32_bf16 v[0:3], v[206:209], v[238:241], v[0:3]
	v_mfma_f32_16x16x32_bf16 v[28:31], v[202:205], v[218:221], v[28:31]
	v_mfma_f32_16x16x32_bf16 v[24:27], v[210:213], v[218:221], v[24:27]
	v_mfma_f32_16x16x32_bf16 v[20:23], v[202:205], v[226:229], v[20:23]
	v_mfma_f32_16x16x32_bf16 v[16:19], v[210:213], v[226:229], v[16:19]
	v_mfma_f32_16x16x32_bf16 v[12:15], v[202:205], v[234:237], v[12:15]
	v_mfma_f32_16x16x32_bf16 v[8:11], v[210:213], v[234:237], v[8:11]
	v_mfma_f32_16x16x32_bf16 v[4:7], v[202:205], v[242:245], v[4:7]
	v_mfma_f32_16x16x32_bf16 v[0:3], v[210:213], v[242:245], v[0:3]
	s_setprio 0
	s_barrier
	s_add_i32 s60, s60, 2
	s_add_u32 s88, s88, 0x100
	s_addc_u32 s89, s89, 0
	s_cmp_lt_u32 s60, 12
	s_cbranch_scc1 .LBB0_24
	ds_read_b128 v[154:157], v138
	ds_read_b128 v[158:161], v139
	ds_read_b128 v[162:165], v140
	ds_read_b128 v[194:197], v141
	ds_read_b128 v[198:201], v142
	ds_read_b128 v[202:205], v143
	ds_read_b128 v[206:209], v144
	ds_read_b128 v[210:213], v145
	s_add_u32 s14, s96, s88
	s_addc_u32 s15, s97, s89
	s_add_u32 s14, s14, 0x4000900
	s_addc_u32 s15, s15, 0
	s_add_u32 s36, s42, s88
	s_addc_u32 s37, s43, s89
	s_cmpk_eq_i32 s88, 0x700
	s_cselect_b32 s27, s87, s15
	s_cselect_b32 s26, s86, s14
	s_cselect_b32 s15, s85, s37
	s_cselect_b32 s14, s84, s36
	v_lshl_add_u64 v[166:167], v[130:131], 0, s[88:89]
	s_add_i32 m0, s94, 0xc000
	ds_read_b128 v[214:217], v137
	ds_read_b128 v[218:221], v137 offset:1024
	ds_read_b128 v[222:225], v137 offset:2048
	ds_read_b128 v[226:229], v137 offset:3072
	ds_read_b128 v[230:233], v137 offset:4096
	ds_read_b128 v[234:237], v137 offset:5120
	ds_read_b128 v[238:241], v137 offset:6144
	ds_read_b128 v[242:245], v137 offset:7168
	global_load_lds_dwordx4 v[166:167], off
	v_lshl_add_u64 v[166:167], v[132:133], 0, s[88:89]
	s_mov_b32 m0, s48
	s_nop 0
	global_load_lds_dwordx4 v[166:167], off
	s_waitcnt vmcnt(8)
	s_waitcnt lgkmcnt(0)
	s_barrier
	s_setprio 1
	s_waitcnt lgkmcnt(0)
	v_mfma_f32_16x16x32_bf16 v[124:127], v[154:157], v[214:217], v[124:127]
	v_mfma_f32_16x16x32_bf16 v[120:123], v[162:165], v[214:217], v[120:123]
	v_mfma_f32_16x16x32_bf16 v[116:119], v[154:157], v[222:225], v[116:119]
	v_mfma_f32_16x16x32_bf16 v[112:115], v[162:165], v[222:225], v[112:115]
	v_mfma_f32_16x16x32_bf16 v[108:111], v[154:157], v[230:233], v[108:111]
	v_mfma_f32_16x16x32_bf16 v[104:107], v[162:165], v[230:233], v[104:107]
	v_mfma_f32_16x16x32_bf16 v[76:79], v[154:157], v[238:241], v[76:79]
	v_mfma_f32_16x16x32_bf16 v[72:75], v[162:165], v[238:241], v[72:75]
	v_mfma_f32_16x16x32_bf16 v[124:127], v[158:161], v[218:221], v[124:127]
	v_mfma_f32_16x16x32_bf16 v[120:123], v[194:197], v[218:221], v[120:123]
	v_mfma_f32_16x16x32_bf16 v[116:119], v[158:161], v[226:229], v[116:119]
	v_mfma_f32_16x16x32_bf16 v[112:115], v[194:197], v[226:229], v[112:115]
	v_mfma_f32_16x16x32_bf16 v[108:111], v[158:161], v[234:237], v[108:111]
	v_mfma_f32_16x16x32_bf16 v[104:107], v[194:197], v[234:237], v[104:107]
	v_mfma_f32_16x16x32_bf16 v[76:79], v[158:161], v[242:245], v[76:79]
	v_mfma_f32_16x16x32_bf16 v[72:75], v[194:197], v[242:245], v[72:75]
	s_setprio 0
	s_setprio 1
	v_mfma_f32_16x16x32_bf16 v[100:103], v[198:201], v[214:217], v[100:103]
	v_mfma_f32_16x16x32_bf16 v[96:99], v[206:209], v[214:217], v[96:99]
	v_mfma_f32_16x16x32_bf16 v[92:95], v[198:201], v[222:225], v[92:95]
	v_mfma_f32_16x16x32_bf16 v[88:91], v[206:209], v[222:225], v[88:91]
	v_mfma_f32_16x16x32_bf16 v[84:87], v[198:201], v[230:233], v[84:87]
	v_mfma_f32_16x16x32_bf16 v[80:83], v[206:209], v[230:233], v[80:83]
	v_mfma_f32_16x16x32_bf16 v[52:55], v[198:201], v[238:241], v[52:55]
	v_mfma_f32_16x16x32_bf16 v[44:47], v[206:209], v[238:241], v[44:47]
	v_mfma_f32_16x16x32_bf16 v[100:103], v[202:205], v[218:221], v[100:103]
	v_mfma_f32_16x16x32_bf16 v[96:99], v[210:213], v[218:221], v[96:99]
	v_mfma_f32_16x16x32_bf16 v[92:95], v[202:205], v[226:229], v[92:95]
	v_mfma_f32_16x16x32_bf16 v[88:91], v[210:213], v[226:229], v[88:91]
	v_mfma_f32_16x16x32_bf16 v[84:87], v[202:205], v[234:237], v[84:87]
	v_mfma_f32_16x16x32_bf16 v[80:83], v[210:213], v[234:237], v[80:83]
	v_mfma_f32_16x16x32_bf16 v[52:55], v[202:205], v[242:245], v[52:55]
	v_mfma_f32_16x16x32_bf16 v[44:47], v[210:213], v[242:245], v[44:47]
	s_setprio 0
	s_barrier
	s_mov_b32 m0, s41
	v_lshl_add_u64 v[166:167], s[14:15], 0, v[168:169]
	s_add_u32 s36, s14, 0x40000
	ds_read_b128 v[214:217], v137 offset:16384
	ds_read_b128 v[218:221], v137 offset:17408
	ds_read_b128 v[222:225], v137 offset:18432
	ds_read_b128 v[226:229], v137 offset:19456
	ds_read_b128 v[230:233], v137 offset:20480
	ds_read_b128 v[234:237], v137 offset:21504
	ds_read_b128 v[238:241], v137 offset:22528
	ds_read_b128 v[242:245], v137 offset:23552
	v_lshl_add_u64 v[246:247], s[14:15], 0, v[128:129]
	s_mov_b32 m0, s59
	s_addc_u32 s37, s15, 0
	v_lshl_add_u64 v[248:249], s[36:37], 0, v[168:169]
	s_mov_b32 m0, s95
	v_lshl_add_u64 v[250:251], s[26:27], 0, v[128:129]
	v_lshl_add_u64 v[248:249], s[36:37], 0, v[128:129]
	s_mov_b32 m0, vcc_lo
	s_nop 0
	v_lshl_add_u64 v[248:249], s[26:27], 0, v[168:169]
	s_mov_b32 m0, s94
	s_nop 0
	s_mov_b32 m0, vcc_hi
	s_nop 0
	s_waitcnt vmcnt(2)
	s_waitcnt lgkmcnt(0)
	s_barrier
	s_setprio 1
	s_waitcnt lgkmcnt(0)
	v_mfma_f32_16x16x32_bf16 v[68:71], v[154:157], v[214:217], v[68:71]
	v_mfma_f32_16x16x32_bf16 v[64:67], v[162:165], v[214:217], v[64:67]
	v_mfma_f32_16x16x32_bf16 v[60:63], v[154:157], v[222:225], v[60:63]
	v_mfma_f32_16x16x32_bf16 v[56:59], v[162:165], v[222:225], v[56:59]
	v_mfma_f32_16x16x32_bf16 v[48:51], v[154:157], v[230:233], v[48:51]
	v_mfma_f32_16x16x32_bf16 v[40:43], v[162:165], v[230:233], v[40:43]
	v_mfma_f32_16x16x32_bf16 v[36:39], v[154:157], v[238:241], v[36:39]
	v_mfma_f32_16x16x32_bf16 v[32:35], v[162:165], v[238:241], v[32:35]
	v_mfma_f32_16x16x32_bf16 v[68:71], v[158:161], v[218:221], v[68:71]
	v_mfma_f32_16x16x32_bf16 v[64:67], v[194:197], v[218:221], v[64:67]
	v_mfma_f32_16x16x32_bf16 v[60:63], v[158:161], v[226:229], v[60:63]
	v_mfma_f32_16x16x32_bf16 v[56:59], v[194:197], v[226:229], v[56:59]
	v_mfma_f32_16x16x32_bf16 v[48:51], v[158:161], v[234:237], v[48:51]
	v_mfma_f32_16x16x32_bf16 v[40:43], v[194:197], v[234:237], v[40:43]
	v_mfma_f32_16x16x32_bf16 v[36:39], v[158:161], v[242:245], v[36:39]
	v_mfma_f32_16x16x32_bf16 v[32:35], v[194:197], v[242:245], v[32:35]
	s_setprio 0
	s_setprio 1
	v_mfma_f32_16x16x32_bf16 v[28:31], v[198:201], v[214:217], v[28:31]
	v_mfma_f32_16x16x32_bf16 v[24:27], v[206:209], v[214:217], v[24:27]
	v_mfma_f32_16x16x32_bf16 v[20:23], v[198:201], v[222:225], v[20:23]
	v_mfma_f32_16x16x32_bf16 v[16:19], v[206:209], v[222:225], v[16:19]
	v_mfma_f32_16x16x32_bf16 v[12:15], v[198:201], v[230:233], v[12:15]
	v_mfma_f32_16x16x32_bf16 v[8:11], v[206:209], v[230:233], v[8:11]
	v_mfma_f32_16x16x32_bf16 v[4:7], v[198:201], v[238:241], v[4:7]
	v_mfma_f32_16x16x32_bf16 v[0:3], v[206:209], v[238:241], v[0:3]
	v_mfma_f32_16x16x32_bf16 v[28:31], v[202:205], v[218:221], v[28:31]
	v_mfma_f32_16x16x32_bf16 v[24:27], v[210:213], v[218:221], v[24:27]
	v_mfma_f32_16x16x32_bf16 v[20:23], v[202:205], v[226:229], v[20:23]
	v_mfma_f32_16x16x32_bf16 v[16:19], v[210:213], v[226:229], v[16:19]
	v_mfma_f32_16x16x32_bf16 v[12:15], v[202:205], v[234:237], v[12:15]
	v_mfma_f32_16x16x32_bf16 v[8:11], v[210:213], v[234:237], v[8:11]
	v_mfma_f32_16x16x32_bf16 v[4:7], v[202:205], v[242:245], v[4:7]
	v_mfma_f32_16x16x32_bf16 v[0:3], v[210:213], v[242:245], v[0:3]
	s_setprio 0
	s_barrier
	ds_read_b128 v[154:157], v146
	ds_read_b128 v[158:161], v147
	ds_read_b128 v[162:165], v148
	ds_read_b128 v[194:197], v149
	ds_read_b128 v[198:201], v150
	ds_read_b128 v[202:205], v151
	ds_read_b128 v[206:209], v152
	ds_read_b128 v[210:213], v153
	s_add_u32 s26, s26, 0x40000
	s_addc_u32 s27, s27, 0
	s_mov_b32 m0, s28
	v_lshl_add_u64 v[180:181], s[26:27], 0, v[168:169]
	ds_read_b128 v[214:217], v137 offset:32768
	ds_read_b128 v[218:221], v137 offset:33792
	ds_read_b128 v[222:225], v137 offset:34816
	ds_read_b128 v[226:229], v137 offset:35840
	ds_read_b128 v[230:233], v137 offset:36864
	ds_read_b128 v[234:237], v137 offset:37888
	ds_read_b128 v[238:241], v137 offset:38912
	ds_read_b128 v[242:245], v137 offset:39936
	v_lshl_add_u64 v[180:181], s[26:27], 0, v[128:129]
	s_mov_b32 m0, s29
	s_nop 0
	s_waitcnt vmcnt(0)
	s_waitcnt lgkmcnt(0)
	s_barrier
	s_setprio 1
	s_waitcnt lgkmcnt(0)
	v_mfma_f32_16x16x32_bf16 v[124:127], v[154:157], v[214:217], v[124:127]
	v_mfma_f32_16x16x32_bf16 v[120:123], v[162:165], v[214:217], v[120:123]
	v_mfma_f32_16x16x32_bf16 v[116:119], v[154:157], v[222:225], v[116:119]
	v_mfma_f32_16x16x32_bf16 v[112:115], v[162:165], v[222:225], v[112:115]
	v_mfma_f32_16x16x32_bf16 v[108:111], v[154:157], v[230:233], v[108:111]
	v_mfma_f32_16x16x32_bf16 v[104:107], v[162:165], v[230:233], v[104:107]
	v_mfma_f32_16x16x32_bf16 v[76:79], v[154:157], v[238:241], v[76:79]
	v_mfma_f32_16x16x32_bf16 v[72:75], v[162:165], v[238:241], v[72:75]
	v_mfma_f32_16x16x32_bf16 v[124:127], v[158:161], v[218:221], v[124:127]
	v_mfma_f32_16x16x32_bf16 v[120:123], v[194:197], v[218:221], v[120:123]
	v_mfma_f32_16x16x32_bf16 v[116:119], v[158:161], v[226:229], v[116:119]
	v_mfma_f32_16x16x32_bf16 v[112:115], v[194:197], v[226:229], v[112:115]
	v_mfma_f32_16x16x32_bf16 v[108:111], v[158:161], v[234:237], v[108:111]
	v_mfma_f32_16x16x32_bf16 v[104:107], v[194:197], v[234:237], v[104:107]
	v_mfma_f32_16x16x32_bf16 v[76:79], v[158:161], v[242:245], v[76:79]
	v_mfma_f32_16x16x32_bf16 v[72:75], v[194:197], v[242:245], v[72:75]
	s_setprio 0
	s_setprio 1
	v_mfma_f32_16x16x32_bf16 v[100:103], v[198:201], v[214:217], v[100:103]
	v_mfma_f32_16x16x32_bf16 v[96:99], v[206:209], v[214:217], v[96:99]
	v_mfma_f32_16x16x32_bf16 v[92:95], v[198:201], v[222:225], v[92:95]
	v_mfma_f32_16x16x32_bf16 v[88:91], v[206:209], v[222:225], v[88:91]
	v_mfma_f32_16x16x32_bf16 v[84:87], v[198:201], v[230:233], v[84:87]
	v_mfma_f32_16x16x32_bf16 v[80:83], v[206:209], v[230:233], v[80:83]
	v_mfma_f32_16x16x32_bf16 v[52:55], v[198:201], v[238:241], v[52:55]
	v_mfma_f32_16x16x32_bf16 v[44:47], v[206:209], v[238:241], v[44:47]
	v_mfma_f32_16x16x32_bf16 v[100:103], v[202:205], v[218:221], v[100:103]
	v_mfma_f32_16x16x32_bf16 v[96:99], v[210:213], v[218:221], v[96:99]
	v_mfma_f32_16x16x32_bf16 v[92:95], v[202:205], v[226:229], v[92:95]
	v_mfma_f32_16x16x32_bf16 v[88:91], v[210:213], v[226:229], v[88:91]
	v_mfma_f32_16x16x32_bf16 v[84:87], v[202:205], v[234:237], v[84:87]
	v_mfma_f32_16x16x32_bf16 v[80:83], v[210:213], v[234:237], v[80:83]
	v_mfma_f32_16x16x32_bf16 v[52:55], v[202:205], v[242:245], v[52:55]
	v_mfma_f32_16x16x32_bf16 v[44:47], v[210:213], v[242:245], v[44:47]
	s_setprio 0
	s_barrier
	s_mov_b32 m0, s19
	v_lshl_add_u64 v[166:167], v[166:167], 0, s[34:35]
	s_add_u32 s14, s14, 0x40080
	ds_read_b128 v[214:217], v137 offset:49152
	ds_read_b128 v[218:221], v137 offset:50176
	ds_read_b128 v[222:225], v137 offset:51200
	ds_read_b128 v[226:229], v137 offset:52224
	ds_read_b128 v[230:233], v137 offset:53248
	ds_read_b128 v[234:237], v137 offset:54272
	ds_read_b128 v[238:241], v137 offset:55296
	ds_read_b128 v[242:245], v137 offset:56320
	v_lshl_add_u64 v[166:167], v[246:247], 0, s[34:35]
	s_mov_b32 m0, s30
	s_addc_u32 s15, s15, 0
	v_lshl_add_u64 v[166:167], s[14:15], 0, v[168:169]
	s_mov_b32 m0, s63
	s_nop 0
	v_lshl_add_u64 v[166:167], s[14:15], 0, v[128:129]
	s_mov_b32 m0, s24
	s_nop 0
	v_lshl_add_u64 v[166:167], v[248:249], 0, s[34:35]
	s_mov_b32 m0, s61
	s_nop 0
	v_lshl_add_u64 v[166:167], v[250:251], 0, s[34:35]
	s_mov_b32 m0, s62
	s_nop 0
	s_waitcnt vmcnt(0)
	s_waitcnt lgkmcnt(0)
	s_barrier
	s_setprio 1
	s_waitcnt lgkmcnt(0)
	v_mfma_f32_16x16x32_bf16 v[68:71], v[154:157], v[214:217], v[68:71]
	v_mfma_f32_16x16x32_bf16 v[64:67], v[162:165], v[214:217], v[64:67]
	v_mfma_f32_16x16x32_bf16 v[60:63], v[154:157], v[222:225], v[60:63]
	v_mfma_f32_16x16x32_bf16 v[56:59], v[162:165], v[222:225], v[56:59]
	v_mfma_f32_16x16x32_bf16 v[48:51], v[154:157], v[230:233], v[48:51]
	v_mfma_f32_16x16x32_bf16 v[40:43], v[162:165], v[230:233], v[40:43]
	v_mfma_f32_16x16x32_bf16 v[36:39], v[154:157], v[238:241], v[36:39]
	v_mfma_f32_16x16x32_bf16 v[32:35], v[162:165], v[238:241], v[32:35]
	v_mfma_f32_16x16x32_bf16 v[68:71], v[158:161], v[218:221], v[68:71]
	v_mfma_f32_16x16x32_bf16 v[64:67], v[194:197], v[218:221], v[64:67]
	v_mfma_f32_16x16x32_bf16 v[60:63], v[158:161], v[226:229], v[60:63]
	v_mfma_f32_16x16x32_bf16 v[56:59], v[194:197], v[226:229], v[56:59]
	v_mfma_f32_16x16x32_bf16 v[48:51], v[158:161], v[234:237], v[48:51]
	v_mfma_f32_16x16x32_bf16 v[40:43], v[194:197], v[234:237], v[40:43]
	v_mfma_f32_16x16x32_bf16 v[36:39], v[158:161], v[242:245], v[36:39]
	v_mfma_f32_16x16x32_bf16 v[32:35], v[194:197], v[242:245], v[32:35]
	s_setprio 0
	s_setprio 1
	v_mfma_f32_16x16x32_bf16 v[28:31], v[198:201], v[214:217], v[28:31]
	v_mfma_f32_16x16x32_bf16 v[24:27], v[206:209], v[214:217], v[24:27]
	v_mfma_f32_16x16x32_bf16 v[20:23], v[198:201], v[222:225], v[20:23]
	v_mfma_f32_16x16x32_bf16 v[16:19], v[206:209], v[222:225], v[16:19]
	v_mfma_f32_16x16x32_bf16 v[12:15], v[198:201], v[230:233], v[12:15]
	v_mfma_f32_16x16x32_bf16 v[8:11], v[206:209], v[230:233], v[8:11]
	v_mfma_f32_16x16x32_bf16 v[4:7], v[198:201], v[238:241], v[4:7]
	v_mfma_f32_16x16x32_bf16 v[0:3], v[206:209], v[238:241], v[0:3]
	v_mfma_f32_16x16x32_bf16 v[28:31], v[202:205], v[218:221], v[28:31]
	v_mfma_f32_16x16x32_bf16 v[24:27], v[210:213], v[218:221], v[24:27]
	v_mfma_f32_16x16x32_bf16 v[20:23], v[202:205], v[226:229], v[20:23]
	v_mfma_f32_16x16x32_bf16 v[16:19], v[210:213], v[226:229], v[16:19]
	v_mfma_f32_16x16x32_bf16 v[12:15], v[202:205], v[234:237], v[12:15]
	v_mfma_f32_16x16x32_bf16 v[8:11], v[210:213], v[234:237], v[8:11]
	v_mfma_f32_16x16x32_bf16 v[4:7], v[202:205], v[242:245], v[4:7]
	v_mfma_f32_16x16x32_bf16 v[0:3], v[210:213], v[242:245], v[0:3]
	s_setprio 0
	s_barrier
	s_add_i32 s60, s60, 2
	s_add_u32 s88, s88, 0x100
	s_addc_u32 s89, s89, 0
	s_cmp_lt_u32 s60, 14
	s_waitcnt vmcnt(0)
	s_cmpk_gt_u32 s92, 0xff
	s_cbranch_scc1 .LBB0_27
	s_barrier

.Lp4_skip_b0:
	s_waitcnt vmcnt(0)
	s_branch .LBB0_41
	s_nop 0
	s_nop 0
	s_nop 0
	s_nop 0
.LBB0_47:
	s_mov_b64 s[42:43], -1

.LBB0_76:
	s_add_i32 s36, s14, 2
	s_add_u32 s48, s26, 0x100
	s_addc_u32 s49, s27, 0
	v_or_b32_e32 v138, 0x10000, v136
	v_add_u32_e32 v142, 0x10400, v136
	v_add_u32_e32 v146, 0x10800, v136
	v_add_u32_e32 v150, 0x10c00, v136
	v_or_b32_e32 v154, 0x14000, v136
	v_add_u32_e32 v158, 0x14400, v136
	v_add_u32_e32 v162, 0x14800, v136
	s_cmp_lg_u32 s63, s14
	ds_read_b128 v[138:141], v138
	ds_read_b128 v[142:145], v142
	ds_read_b128 v[146:149], v146
	ds_read_b128 v[150:153], v150
	ds_read_b128 v[154:157], v154
	ds_read_b128 v[158:161], v158
	v_add_u32_e32 v166, 0x14c00, v136
	ds_read_b128 v[162:165], v162
	ds_read_b128 v[194:197], v166
	s_cselect_b32 s44, s48, 0
	s_cselect_b32 s37, s49, 0
	s_add_u32 s14, s42, s44
	s_addc_u32 s15, s43, s37
	s_add_u32 s44, s40, s44
	s_addc_u32 s45, s41, s37
	v_lshl_add_u64 v[166:167], v[130:131], 0, s[26:27]
	s_add_i32 m0, s90, 0xc000
	ds_read_b128 v[198:201], v137
	ds_read_b128 v[202:205], v137 offset:1024
	ds_read_b128 v[206:209], v137 offset:2048
	ds_read_b128 v[210:213], v137 offset:3072
	ds_read_b128 v[214:217], v137 offset:4096
	ds_read_b128 v[218:221], v137 offset:5120
	ds_read_b128 v[222:225], v137 offset:6144
	ds_read_b128 v[226:229], v137 offset:7168
	global_load_lds_dwordx4 v[166:167], off
	v_lshl_add_u64 v[166:167], v[132:133], 0, s[26:27]
	s_add_i32 m0, s90, 0xe000
	s_nop 0
	global_load_lds_dwordx4 v[166:167], off
	s_waitcnt vmcnt(8)
	s_waitcnt lgkmcnt(0)
	s_barrier
	s_setprio 1
	s_waitcnt lgkmcnt(0)
	v_mfma_f32_16x16x32_bf16 v[124:127], v[138:141], v[198:201], v[124:127]
	v_mfma_f32_16x16x32_bf16 v[120:123], v[146:149], v[198:201], v[120:123]
	v_mfma_f32_16x16x32_bf16 v[116:119], v[138:141], v[206:209], v[116:119]
	v_mfma_f32_16x16x32_bf16 v[112:115], v[146:149], v[206:209], v[112:115]
	v_mfma_f32_16x16x32_bf16 v[108:111], v[138:141], v[214:217], v[108:111]
	v_mfma_f32_16x16x32_bf16 v[104:107], v[146:149], v[214:217], v[104:107]
	v_mfma_f32_16x16x32_bf16 v[100:103], v[138:141], v[222:225], v[100:103]
	v_mfma_f32_16x16x32_bf16 v[96:99], v[146:149], v[222:225], v[96:99]
	v_mfma_f32_16x16x32_bf16 v[124:127], v[142:145], v[202:205], v[124:127]
	v_mfma_f32_16x16x32_bf16 v[120:123], v[150:153], v[202:205], v[120:123]
	v_mfma_f32_16x16x32_bf16 v[116:119], v[142:145], v[210:213], v[116:119]
	v_mfma_f32_16x16x32_bf16 v[112:115], v[150:153], v[210:213], v[112:115]
	v_mfma_f32_16x16x32_bf16 v[108:111], v[142:145], v[218:221], v[108:111]
	v_mfma_f32_16x16x32_bf16 v[104:107], v[150:153], v[218:221], v[104:107]
	v_mfma_f32_16x16x32_bf16 v[100:103], v[142:145], v[226:229], v[100:103]
	v_mfma_f32_16x16x32_bf16 v[96:99], v[150:153], v[226:229], v[96:99]
	s_setprio 0
	s_setprio 1
	v_mfma_f32_16x16x32_bf16 v[92:95], v[154:157], v[198:201], v[92:95]
	v_mfma_f32_16x16x32_bf16 v[88:91], v[162:165], v[198:201], v[88:91]
	v_mfma_f32_16x16x32_bf16 v[84:87], v[154:157], v[206:209], v[84:87]
	v_mfma_f32_16x16x32_bf16 v[80:83], v[162:165], v[206:209], v[80:83]
	v_mfma_f32_16x16x32_bf16 v[76:79], v[154:157], v[214:217], v[76:79]
	v_mfma_f32_16x16x32_bf16 v[72:75], v[162:165], v[214:217], v[72:75]
	v_mfma_f32_16x16x32_bf16 v[68:71], v[154:157], v[222:225], v[68:71]
	v_mfma_f32_16x16x32_bf16 v[64:67], v[162:165], v[222:225], v[64:67]
	v_mfma_f32_16x16x32_bf16 v[92:95], v[158:161], v[202:205], v[92:95]
	v_mfma_f32_16x16x32_bf16 v[88:91], v[194:197], v[202:205], v[88:91]
	v_mfma_f32_16x16x32_bf16 v[84:87], v[158:161], v[210:213], v[84:87]
	v_mfma_f32_16x16x32_bf16 v[80:83], v[194:197], v[210:213], v[80:83]
	v_mfma_f32_16x16x32_bf16 v[76:79], v[158:161], v[218:221], v[76:79]
	v_mfma_f32_16x16x32_bf16 v[72:75], v[194:197], v[218:221], v[72:75]
	v_mfma_f32_16x16x32_bf16 v[68:71], v[158:161], v[226:229], v[68:71]
	v_mfma_f32_16x16x32_bf16 v[64:67], v[194:197], v[226:229], v[64:67]
	s_setprio 0
	s_barrier
	s_mov_b32 m0, s28
	v_lshl_add_u64 v[166:167], s[44:45], 0, v[168:169]
	s_add_u32 s26, s44, s56
	ds_read_b128 v[198:201], v137 offset:16384
	ds_read_b128 v[202:205], v137 offset:17408
	ds_read_b128 v[206:209], v137 offset:18432
	ds_read_b128 v[210:213], v137 offset:19456
	ds_read_b128 v[214:217], v137 offset:20480
	ds_read_b128 v[218:221], v137 offset:21504
	ds_read_b128 v[222:225], v137 offset:22528
	ds_read_b128 v[226:229], v137 offset:23552
	global_load_lds_dwordx4 v[166:167], off
	v_lshl_add_u64 v[230:231], s[44:45], 0, v[128:129]
	s_mov_b32 m0, s29
	s_addc_u32 s27, s45, 0
	global_load_lds_dwordx4 v[230:231], off
	v_lshl_add_u64 v[232:233], s[26:27], 0, v[168:169]
	s_mov_b32 m0, s91
	v_lshl_add_u64 v[234:235], s[26:27], 0, v[128:129]
	global_load_lds_dwordx4 v[232:233], off
	s_mov_b32 m0, s92
	v_lshl_add_u64 v[236:237], s[14:15], 0, v[168:169]
	global_load_lds_dwordx4 v[234:235], off
	s_mov_b32 m0, s90
	v_lshl_add_u64 v[238:239], s[14:15], 0, v[128:129]
	global_load_lds_dwordx4 v[236:237], off
	s_mov_b32 m0, s93
	s_nop 0
	global_load_lds_dwordx4 v[238:239], off
	s_waitcnt vmcnt(8)
	s_waitcnt lgkmcnt(0)
	s_barrier
	s_setprio 1
	s_waitcnt lgkmcnt(0)
	v_mfma_f32_16x16x32_bf16 v[60:63], v[138:141], v[198:201], v[60:63]
	v_mfma_f32_16x16x32_bf16 v[56:59], v[146:149], v[198:201], v[56:59]
	v_mfma_f32_16x16x32_bf16 v[52:55], v[138:141], v[206:209], v[52:55]
	v_mfma_f32_16x16x32_bf16 v[48:51], v[146:149], v[206:209], v[48:51]
	v_mfma_f32_16x16x32_bf16 v[44:47], v[138:141], v[214:217], v[44:47]
	v_mfma_f32_16x16x32_bf16 v[40:43], v[146:149], v[214:217], v[40:43]
	v_mfma_f32_16x16x32_bf16 v[36:39], v[138:141], v[222:225], v[36:39]
	v_mfma_f32_16x16x32_bf16 v[32:35], v[146:149], v[222:225], v[32:35]
	v_mfma_f32_16x16x32_bf16 v[60:63], v[142:145], v[202:205], v[60:63]
	v_mfma_f32_16x16x32_bf16 v[56:59], v[150:153], v[202:205], v[56:59]
	v_mfma_f32_16x16x32_bf16 v[52:55], v[142:145], v[210:213], v[52:55]
	v_mfma_f32_16x16x32_bf16 v[48:51], v[150:153], v[210:213], v[48:51]
	v_mfma_f32_16x16x32_bf16 v[44:47], v[142:145], v[218:221], v[44:47]
	v_mfma_f32_16x16x32_bf16 v[40:43], v[150:153], v[218:221], v[40:43]
	v_mfma_f32_16x16x32_bf16 v[36:39], v[142:145], v[226:229], v[36:39]
	v_mfma_f32_16x16x32_bf16 v[32:35], v[150:153], v[226:229], v[32:35]
	s_setprio 0
	s_setprio 1
	v_mfma_f32_16x16x32_bf16 v[28:31], v[154:157], v[198:201], v[28:31]
	v_mfma_f32_16x16x32_bf16 v[24:27], v[162:165], v[198:201], v[24:27]
	v_mfma_f32_16x16x32_bf16 v[20:23], v[154:157], v[206:209], v[20:23]
	v_mfma_f32_16x16x32_bf16 v[16:19], v[162:165], v[206:209], v[16:19]
	v_mfma_f32_16x16x32_bf16 v[12:15], v[154:157], v[214:217], v[12:15]
	v_mfma_f32_16x16x32_bf16 v[8:11], v[162:165], v[214:217], v[8:11]
	v_mfma_f32_16x16x32_bf16 v[4:7], v[154:157], v[222:225], v[4:7]
	v_mfma_f32_16x16x32_bf16 v[0:3], v[162:165], v[222:225], v[0:3]
	v_mfma_f32_16x16x32_bf16 v[28:31], v[158:161], v[202:205], v[28:31]
	v_mfma_f32_16x16x32_bf16 v[24:27], v[194:197], v[202:205], v[24:27]
	v_mfma_f32_16x16x32_bf16 v[20:23], v[158:161], v[210:213], v[20:23]
	v_mfma_f32_16x16x32_bf16 v[16:19], v[194:197], v[210:213], v[16:19]
	v_mfma_f32_16x16x32_bf16 v[12:15], v[158:161], v[218:221], v[12:15]
	v_mfma_f32_16x16x32_bf16 v[8:11], v[194:197], v[218:221], v[8:11]
	v_mfma_f32_16x16x32_bf16 v[4:7], v[158:161], v[226:229], v[4:7]
	v_mfma_f32_16x16x32_bf16 v[0:3], v[194:197], v[226:229], v[0:3]
	s_setprio 0
	s_barrier
	v_or_b32_e32 v138, 0x18000, v136
	v_add_u32_e32 v142, 0x18400, v136
	v_add_u32_e32 v146, 0x18800, v136
	v_add_u32_e32 v150, 0x18c00, v136
	v_or_b32_e32 v154, 0x1c000, v136
	v_add_u32_e32 v158, 0x1c400, v136
	v_add_u32_e32 v162, 0x1c800, v136
	ds_read_b128 v[138:141], v138
	ds_read_b128 v[142:145], v142
	ds_read_b128 v[146:149], v146
	ds_read_b128 v[150:153], v150
	ds_read_b128 v[154:157], v154
	ds_read_b128 v[158:161], v158
	v_add_u32_e32 v180, 0x1cc00, v136
	ds_read_b128 v[162:165], v162
	ds_read_b128 v[194:197], v180
	s_add_u32 s14, s14, s56
	s_addc_u32 s15, s15, 0
	s_mov_b32 m0, s94
	v_lshl_add_u64 v[240:241], s[14:15], 0, v[168:169]
	ds_read_b128 v[198:201], v137 offset:32768
	ds_read_b128 v[202:205], v137 offset:33792
	ds_read_b128 v[206:209], v137 offset:34816
	ds_read_b128 v[210:213], v137 offset:35840
	ds_read_b128 v[214:217], v137 offset:36864
	ds_read_b128 v[218:221], v137 offset:37888
	ds_read_b128 v[222:225], v137 offset:38912
	ds_read_b128 v[226:229], v137 offset:39936
	global_load_lds_dwordx4 v[240:241], off
	v_lshl_add_u64 v[240:241], s[14:15], 0, v[128:129]
	s_mov_b32 m0, vcc_lo
	s_nop 0
	global_load_lds_dwordx4 v[240:241], off
	s_waitcnt vmcnt(8)
	s_waitcnt lgkmcnt(0)
	s_barrier
	s_setprio 1
	s_waitcnt lgkmcnt(0)
	v_mfma_f32_16x16x32_bf16 v[124:127], v[138:141], v[198:201], v[124:127]
	v_mfma_f32_16x16x32_bf16 v[120:123], v[146:149], v[198:201], v[120:123]
	v_mfma_f32_16x16x32_bf16 v[116:119], v[138:141], v[206:209], v[116:119]
	v_mfma_f32_16x16x32_bf16 v[112:115], v[146:149], v[206:209], v[112:115]
	v_mfma_f32_16x16x32_bf16 v[108:111], v[138:141], v[214:217], v[108:111]
	v_mfma_f32_16x16x32_bf16 v[104:107], v[146:149], v[214:217], v[104:107]
	v_mfma_f32_16x16x32_bf16 v[100:103], v[138:141], v[222:225], v[100:103]
	v_mfma_f32_16x16x32_bf16 v[96:99], v[146:149], v[222:225], v[96:99]
	v_mfma_f32_16x16x32_bf16 v[124:127], v[142:145], v[202:205], v[124:127]
	v_mfma_f32_16x16x32_bf16 v[120:123], v[150:153], v[202:205], v[120:123]
	v_mfma_f32_16x16x32_bf16 v[116:119], v[142:145], v[210:213], v[116:119]
	v_mfma_f32_16x16x32_bf16 v[112:115], v[150:153], v[210:213], v[112:115]
	v_mfma_f32_16x16x32_bf16 v[108:111], v[142:145], v[218:221], v[108:111]
	v_mfma_f32_16x16x32_bf16 v[104:107], v[150:153], v[218:221], v[104:107]
	v_mfma_f32_16x16x32_bf16 v[100:103], v[142:145], v[226:229], v[100:103]
	v_mfma_f32_16x16x32_bf16 v[96:99], v[150:153], v[226:229], v[96:99]
	s_setprio 0
	s_setprio 1
	v_mfma_f32_16x16x32_bf16 v[92:95], v[154:157], v[198:201], v[92:95]
	v_mfma_f32_16x16x32_bf16 v[88:91], v[162:165], v[198:201], v[88:91]
	v_mfma_f32_16x16x32_bf16 v[84:87], v[154:157], v[206:209], v[84:87]
	v_mfma_f32_16x16x32_bf16 v[80:83], v[162:165], v[206:209], v[80:83]
	v_mfma_f32_16x16x32_bf16 v[76:79], v[154:157], v[214:217], v[76:79]
	v_mfma_f32_16x16x32_bf16 v[72:75], v[162:165], v[214:217], v[72:75]
	v_mfma_f32_16x16x32_bf16 v[68:71], v[154:157], v[222:225], v[68:71]
	v_mfma_f32_16x16x32_bf16 v[64:67], v[162:165], v[222:225], v[64:67]
	v_mfma_f32_16x16x32_bf16 v[92:95], v[158:161], v[202:205], v[92:95]
	v_mfma_f32_16x16x32_bf16 v[88:91], v[194:197], v[202:205], v[88:91]
	v_mfma_f32_16x16x32_bf16 v[84:87], v[158:161], v[210:213], v[84:87]
	v_mfma_f32_16x16x32_bf16 v[80:83], v[194:197], v[210:213], v[80:83]
	v_mfma_f32_16x16x32_bf16 v[76:79], v[158:161], v[218:221], v[76:79]
	v_mfma_f32_16x16x32_bf16 v[72:75], v[194:197], v[218:221], v[72:75]
	v_mfma_f32_16x16x32_bf16 v[68:71], v[158:161], v[226:229], v[68:71]
	v_mfma_f32_16x16x32_bf16 v[64:67], v[194:197], v[226:229], v[64:67]
	s_setprio 0
	s_barrier
	s_mov_b32 m0, s17
	v_lshl_add_u64 v[166:167], v[166:167], 0, s[34:35]
	ds_read_b128 v[198:201], v137 offset:49152
	ds_read_b128 v[202:205], v137 offset:50176
	ds_read_b128 v[206:209], v137 offset:51200
	ds_read_b128 v[210:213], v137 offset:52224
	ds_read_b128 v[214:217], v137 offset:53248
	ds_read_b128 v[218:221], v137 offset:54272
	ds_read_b128 v[222:225], v137 offset:55296
	ds_read_b128 v[226:229], v137 offset:56320
	global_load_lds_dwordx4 v[166:167], off
	v_lshl_add_u64 v[166:167], v[230:231], 0, s[34:35]
	s_mov_b32 m0, s24
	s_nop 0
	global_load_lds_dwordx4 v[166:167], off
	v_lshl_add_u64 v[166:167], v[232:233], 0, s[34:35]
	s_mov_b32 m0, s97
	s_nop 0
	global_load_lds_dwordx4 v[166:167], off
	v_lshl_add_u64 v[166:167], v[234:235], 0, s[34:35]
	s_mov_b32 m0, vcc_hi
	s_nop 0
	global_load_lds_dwordx4 v[166:167], off
	v_lshl_add_u64 v[166:167], v[236:237], 0, s[34:35]
	s_mov_b32 m0, s60
	s_nop 0
	global_load_lds_dwordx4 v[166:167], off
	v_lshl_add_u64 v[166:167], v[238:239], 0, s[34:35]
	s_mov_b32 m0, s96
	s_nop 0
	global_load_lds_dwordx4 v[166:167], off
	s_waitcnt vmcnt(8)
	s_waitcnt lgkmcnt(0)
	s_barrier
	s_setprio 1
	s_waitcnt lgkmcnt(0)
	v_mfma_f32_16x16x32_bf16 v[60:63], v[138:141], v[198:201], v[60:63]
	v_mfma_f32_16x16x32_bf16 v[56:59], v[146:149], v[198:201], v[56:59]
	v_mfma_f32_16x16x32_bf16 v[52:55], v[138:141], v[206:209], v[52:55]
	v_mfma_f32_16x16x32_bf16 v[48:51], v[146:149], v[206:209], v[48:51]
	v_mfma_f32_16x16x32_bf16 v[44:47], v[138:141], v[214:217], v[44:47]
	v_mfma_f32_16x16x32_bf16 v[40:43], v[146:149], v[214:217], v[40:43]
	v_mfma_f32_16x16x32_bf16 v[36:39], v[138:141], v[222:225], v[36:39]
	v_mfma_f32_16x16x32_bf16 v[32:35], v[146:149], v[222:225], v[32:35]
	v_mfma_f32_16x16x32_bf16 v[60:63], v[142:145], v[202:205], v[60:63]
	v_mfma_f32_16x16x32_bf16 v[56:59], v[150:153], v[202:205], v[56:59]
	v_mfma_f32_16x16x32_bf16 v[52:55], v[142:145], v[210:213], v[52:55]
	v_mfma_f32_16x16x32_bf16 v[48:51], v[150:153], v[210:213], v[48:51]
	v_mfma_f32_16x16x32_bf16 v[44:47], v[142:145], v[218:221], v[44:47]
	v_mfma_f32_16x16x32_bf16 v[40:43], v[150:153], v[218:221], v[40:43]
	v_mfma_f32_16x16x32_bf16 v[36:39], v[142:145], v[226:229], v[36:39]
	v_mfma_f32_16x16x32_bf16 v[32:35], v[150:153], v[226:229], v[32:35]
	s_setprio 0
	s_setprio 1
	v_mfma_f32_16x16x32_bf16 v[28:31], v[154:157], v[198:201], v[28:31]
	v_mfma_f32_16x16x32_bf16 v[24:27], v[162:165], v[198:201], v[24:27]
	v_mfma_f32_16x16x32_bf16 v[20:23], v[154:157], v[206:209], v[20:23]
	v_mfma_f32_16x16x32_bf16 v[16:19], v[162:165], v[206:209], v[16:19]
	v_mfma_f32_16x16x32_bf16 v[12:15], v[154:157], v[214:217], v[12:15]
	v_mfma_f32_16x16x32_bf16 v[8:11], v[162:165], v[214:217], v[8:11]
	v_mfma_f32_16x16x32_bf16 v[4:7], v[154:157], v[222:225], v[4:7]
	v_mfma_f32_16x16x32_bf16 v[0:3], v[162:165], v[222:225], v[0:3]
	v_mfma_f32_16x16x32_bf16 v[28:31], v[158:161], v[202:205], v[28:31]
	v_mfma_f32_16x16x32_bf16 v[24:27], v[194:197], v[202:205], v[24:27]
	v_mfma_f32_16x16x32_bf16 v[20:23], v[158:161], v[210:213], v[20:23]
	v_mfma_f32_16x16x32_bf16 v[16:19], v[194:197], v[210:213], v[16:19]
	v_mfma_f32_16x16x32_bf16 v[12:15], v[158:161], v[218:221], v[12:15]
	v_mfma_f32_16x16x32_bf16 v[8:11], v[194:197], v[218:221], v[8:11]
	v_mfma_f32_16x16x32_bf16 v[4:7], v[158:161], v[226:229], v[4:7]
	v_mfma_f32_16x16x32_bf16 v[0:3], v[194:197], v[226:229], v[0:3]
	s_setprio 0
	s_barrier
	s_cmp_lt_u32 s36, s63
	s_mov_b64 s[26:27], s[48:49]
	s_mov_b32 s14, s36
	s_cbranch_scc1 .LBB0_76
	s_add_i32 s36, s14, 2
	s_add_u32 s48, s26, 0x100
	s_addc_u32 s49, s27, 0
	v_or_b32_e32 v138, 0x10000, v136
	v_add_u32_e32 v142, 0x10400, v136
	v_add_u32_e32 v146, 0x10800, v136
	v_add_u32_e32 v150, 0x10c00, v136
	v_or_b32_e32 v154, 0x14000, v136
	v_add_u32_e32 v158, 0x14400, v136
	v_add_u32_e32 v162, 0x14800, v136
	s_cmp_lg_u32 s63, s14
	ds_read_b128 v[138:141], v138
	ds_read_b128 v[142:145], v142
	ds_read_b128 v[146:149], v146
	ds_read_b128 v[150:153], v150
	ds_read_b128 v[154:157], v154
	ds_read_b128 v[158:161], v158
	v_add_u32_e32 v166, 0x14c00, v136
	ds_read_b128 v[162:165], v162
	ds_read_b128 v[194:197], v166
	s_cselect_b32 s44, s48, 0
	s_cselect_b32 s37, s49, 0
	s_add_u32 s14, s42, s44
	s_addc_u32 s15, s43, s37
	s_add_u32 s44, s40, s44
	s_addc_u32 s45, s41, s37
	v_lshl_add_u64 v[166:167], v[130:131], 0, s[26:27]
	s_add_i32 m0, s90, 0xc000
	ds_read_b128 v[198:201], v137
	ds_read_b128 v[202:205], v137 offset:1024
	ds_read_b128 v[206:209], v137 offset:2048
	ds_read_b128 v[210:213], v137 offset:3072
	ds_read_b128 v[214:217], v137 offset:4096
	ds_read_b128 v[218:221], v137 offset:5120
	ds_read_b128 v[222:225], v137 offset:6144
	ds_read_b128 v[226:229], v137 offset:7168
	global_load_lds_dwordx4 v[166:167], off
	v_lshl_add_u64 v[166:167], v[132:133], 0, s[26:27]
	s_add_i32 m0, s90, 0xe000
	s_nop 0
	global_load_lds_dwordx4 v[166:167], off
	s_waitcnt vmcnt(8)
	s_waitcnt lgkmcnt(0)
	s_barrier
	s_setprio 1
	s_waitcnt lgkmcnt(0)
	v_mfma_f32_16x16x32_bf16 v[124:127], v[138:141], v[198:201], v[124:127]
	v_mfma_f32_16x16x32_bf16 v[120:123], v[146:149], v[198:201], v[120:123]
	v_mfma_f32_16x16x32_bf16 v[116:119], v[138:141], v[206:209], v[116:119]
	v_mfma_f32_16x16x32_bf16 v[112:115], v[146:149], v[206:209], v[112:115]
	v_mfma_f32_16x16x32_bf16 v[108:111], v[138:141], v[214:217], v[108:111]
	v_mfma_f32_16x16x32_bf16 v[104:107], v[146:149], v[214:217], v[104:107]
	v_mfma_f32_16x16x32_bf16 v[100:103], v[138:141], v[222:225], v[100:103]
	v_mfma_f32_16x16x32_bf16 v[96:99], v[146:149], v[222:225], v[96:99]
	v_mfma_f32_16x16x32_bf16 v[124:127], v[142:145], v[202:205], v[124:127]
	v_mfma_f32_16x16x32_bf16 v[120:123], v[150:153], v[202:205], v[120:123]
	v_mfma_f32_16x16x32_bf16 v[116:119], v[142:145], v[210:213], v[116:119]
	v_mfma_f32_16x16x32_bf16 v[112:115], v[150:153], v[210:213], v[112:115]
	v_mfma_f32_16x16x32_bf16 v[108:111], v[142:145], v[218:221], v[108:111]
	v_mfma_f32_16x16x32_bf16 v[104:107], v[150:153], v[218:221], v[104:107]
	v_mfma_f32_16x16x32_bf16 v[100:103], v[142:145], v[226:229], v[100:103]
	v_mfma_f32_16x16x32_bf16 v[96:99], v[150:153], v[226:229], v[96:99]
	s_setprio 0
	s_setprio 1
	v_mfma_f32_16x16x32_bf16 v[92:95], v[154:157], v[198:201], v[92:95]
	v_mfma_f32_16x16x32_bf16 v[88:91], v[162:165], v[198:201], v[88:91]
	v_mfma_f32_16x16x32_bf16 v[84:87], v[154:157], v[206:209], v[84:87]
	v_mfma_f32_16x16x32_bf16 v[80:83], v[162:165], v[206:209], v[80:83]
	v_mfma_f32_16x16x32_bf16 v[76:79], v[154:157], v[214:217], v[76:79]
	v_mfma_f32_16x16x32_bf16 v[72:75], v[162:165], v[214:217], v[72:75]
	v_mfma_f32_16x16x32_bf16 v[68:71], v[154:157], v[222:225], v[68:71]
	v_mfma_f32_16x16x32_bf16 v[64:67], v[162:165], v[222:225], v[64:67]
	v_mfma_f32_16x16x32_bf16 v[92:95], v[158:161], v[202:205], v[92:95]
	v_mfma_f32_16x16x32_bf16 v[88:91], v[194:197], v[202:205], v[88:91]
	v_mfma_f32_16x16x32_bf16 v[84:87], v[158:161], v[210:213], v[84:87]
	v_mfma_f32_16x16x32_bf16 v[80:83], v[194:197], v[210:213], v[80:83]
	v_mfma_f32_16x16x32_bf16 v[76:79], v[158:161], v[218:221], v[76:79]
	v_mfma_f32_16x16x32_bf16 v[72:75], v[194:197], v[218:221], v[72:75]
	v_mfma_f32_16x16x32_bf16 v[68:71], v[158:161], v[226:229], v[68:71]
	v_mfma_f32_16x16x32_bf16 v[64:67], v[194:197], v[226:229], v[64:67]
	s_setprio 0
	s_barrier
	s_mov_b32 m0, s28
	v_lshl_add_u64 v[166:167], s[44:45], 0, v[168:169]
	s_add_u32 s26, s44, s56
	ds_read_b128 v[198:201], v137 offset:16384
	ds_read_b128 v[202:205], v137 offset:17408
	ds_read_b128 v[206:209], v137 offset:18432
	ds_read_b128 v[210:213], v137 offset:19456
	ds_read_b128 v[214:217], v137 offset:20480
	ds_read_b128 v[218:221], v137 offset:21504
	ds_read_b128 v[222:225], v137 offset:22528
	ds_read_b128 v[226:229], v137 offset:23552
	v_lshl_add_u64 v[230:231], s[44:45], 0, v[128:129]
	s_mov_b32 m0, s29
	s_addc_u32 s27, s45, 0
	v_lshl_add_u64 v[232:233], s[26:27], 0, v[168:169]
	s_mov_b32 m0, s91
	v_lshl_add_u64 v[234:235], s[26:27], 0, v[128:129]
	s_mov_b32 m0, s92
	v_lshl_add_u64 v[236:237], s[14:15], 0, v[168:169]
	s_mov_b32 m0, s90
	v_lshl_add_u64 v[238:239], s[14:15], 0, v[128:129]
	s_mov_b32 m0, s93
	s_nop 0
	s_waitcnt vmcnt(2)
	s_waitcnt lgkmcnt(0)
	s_barrier
	s_setprio 1
	s_waitcnt lgkmcnt(0)
	v_mfma_f32_16x16x32_bf16 v[60:63], v[138:141], v[198:201], v[60:63]
	v_mfma_f32_16x16x32_bf16 v[56:59], v[146:149], v[198:201], v[56:59]
	v_mfma_f32_16x16x32_bf16 v[52:55], v[138:141], v[206:209], v[52:55]
	v_mfma_f32_16x16x32_bf16 v[48:51], v[146:149], v[206:209], v[48:51]
	v_mfma_f32_16x16x32_bf16 v[44:47], v[138:141], v[214:217], v[44:47]
	v_mfma_f32_16x16x32_bf16 v[40:43], v[146:149], v[214:217], v[40:43]
	v_mfma_f32_16x16x32_bf16 v[36:39], v[138:141], v[222:225], v[36:39]
	v_mfma_f32_16x16x32_bf16 v[32:35], v[146:149], v[222:225], v[32:35]
	v_mfma_f32_16x16x32_bf16 v[60:63], v[142:145], v[202:205], v[60:63]
	v_mfma_f32_16x16x32_bf16 v[56:59], v[150:153], v[202:205], v[56:59]
	v_mfma_f32_16x16x32_bf16 v[52:55], v[142:145], v[210:213], v[52:55]
	v_mfma_f32_16x16x32_bf16 v[48:51], v[150:153], v[210:213], v[48:51]
	v_mfma_f32_16x16x32_bf16 v[44:47], v[142:145], v[218:221], v[44:47]
	v_mfma_f32_16x16x32_bf16 v[40:43], v[150:153], v[218:221], v[40:43]
	v_mfma_f32_16x16x32_bf16 v[36:39], v[142:145], v[226:229], v[36:39]
	v_mfma_f32_16x16x32_bf16 v[32:35], v[150:153], v[226:229], v[32:35]
	s_setprio 0
	s_setprio 1
	v_mfma_f32_16x16x32_bf16 v[28:31], v[154:157], v[198:201], v[28:31]
	v_mfma_f32_16x16x32_bf16 v[24:27], v[162:165], v[198:201], v[24:27]
	v_mfma_f32_16x16x32_bf16 v[20:23], v[154:157], v[206:209], v[20:23]
	v_mfma_f32_16x16x32_bf16 v[16:19], v[162:165], v[206:209], v[16:19]
	v_mfma_f32_16x16x32_bf16 v[12:15], v[154:157], v[214:217], v[12:15]
	v_mfma_f32_16x16x32_bf16 v[8:11], v[162:165], v[214:217], v[8:11]
	v_mfma_f32_16x16x32_bf16 v[4:7], v[154:157], v[222:225], v[4:7]
	v_mfma_f32_16x16x32_bf16 v[0:3], v[162:165], v[222:225], v[0:3]
	v_mfma_f32_16x16x32_bf16 v[28:31], v[158:161], v[202:205], v[28:31]
	v_mfma_f32_16x16x32_bf16 v[24:27], v[194:197], v[202:205], v[24:27]
	v_mfma_f32_16x16x32_bf16 v[20:23], v[158:161], v[210:213], v[20:23]
	v_mfma_f32_16x16x32_bf16 v[16:19], v[194:197], v[210:213], v[16:19]
	v_mfma_f32_16x16x32_bf16 v[12:15], v[158:161], v[218:221], v[12:15]
	v_mfma_f32_16x16x32_bf16 v[8:11], v[194:197], v[218:221], v[8:11]
	v_mfma_f32_16x16x32_bf16 v[4:7], v[158:161], v[226:229], v[4:7]
	v_mfma_f32_16x16x32_bf16 v[0:3], v[194:197], v[226:229], v[0:3]
	s_setprio 0
	s_barrier
	v_or_b32_e32 v138, 0x18000, v136
	v_add_u32_e32 v142, 0x18400, v136
	v_add_u32_e32 v146, 0x18800, v136
	v_add_u32_e32 v150, 0x18c00, v136
	v_or_b32_e32 v154, 0x1c000, v136
	v_add_u32_e32 v158, 0x1c400, v136
	v_add_u32_e32 v162, 0x1c800, v136
	ds_read_b128 v[138:141], v138
	ds_read_b128 v[142:145], v142
	ds_read_b128 v[146:149], v146
	ds_read_b128 v[150:153], v150
	ds_read_b128 v[154:157], v154
	ds_read_b128 v[158:161], v158
	v_add_u32_e32 v180, 0x1cc00, v136
	ds_read_b128 v[162:165], v162
	ds_read_b128 v[194:197], v180
	s_add_u32 s14, s14, s56
	s_addc_u32 s15, s15, 0
	s_mov_b32 m0, s94
	v_lshl_add_u64 v[240:241], s[14:15], 0, v[168:169]
	ds_read_b128 v[198:201], v137 offset:32768
	ds_read_b128 v[202:205], v137 offset:33792
	ds_read_b128 v[206:209], v137 offset:34816
	ds_read_b128 v[210:213], v137 offset:35840
	ds_read_b128 v[214:217], v137 offset:36864
	ds_read_b128 v[218:221], v137 offset:37888
	ds_read_b128 v[222:225], v137 offset:38912
	ds_read_b128 v[226:229], v137 offset:39936
	v_lshl_add_u64 v[240:241], s[14:15], 0, v[128:129]
	s_mov_b32 m0, vcc_lo
	s_nop 0
	s_waitcnt vmcnt(0)
	s_waitcnt lgkmcnt(0)
	s_barrier
	s_setprio 1
	s_waitcnt lgkmcnt(0)
	v_mfma_f32_16x16x32_bf16 v[124:127], v[138:141], v[198:201], v[124:127]
	v_mfma_f32_16x16x32_bf16 v[120:123], v[146:149], v[198:201], v[120:123]
	v_mfma_f32_16x16x32_bf16 v[116:119], v[138:141], v[206:209], v[116:119]
	v_mfma_f32_16x16x32_bf16 v[112:115], v[146:149], v[206:209], v[112:115]
	v_mfma_f32_16x16x32_bf16 v[108:111], v[138:141], v[214:217], v[108:111]
	v_mfma_f32_16x16x32_bf16 v[104:107], v[146:149], v[214:217], v[104:107]
	v_mfma_f32_16x16x32_bf16 v[100:103], v[138:141], v[222:225], v[100:103]
	v_mfma_f32_16x16x32_bf16 v[96:99], v[146:149], v[222:225], v[96:99]
	v_mfma_f32_16x16x32_bf16 v[124:127], v[142:145], v[202:205], v[124:127]
	v_mfma_f32_16x16x32_bf16 v[120:123], v[150:153], v[202:205], v[120:123]
	v_mfma_f32_16x16x32_bf16 v[116:119], v[142:145], v[210:213], v[116:119]
	v_mfma_f32_16x16x32_bf16 v[112:115], v[150:153], v[210:213], v[112:115]
	v_mfma_f32_16x16x32_bf16 v[108:111], v[142:145], v[218:221], v[108:111]
	v_mfma_f32_16x16x32_bf16 v[104:107], v[150:153], v[218:221], v[104:107]
	v_mfma_f32_16x16x32_bf16 v[100:103], v[142:145], v[226:229], v[100:103]
	v_mfma_f32_16x16x32_bf16 v[96:99], v[150:153], v[226:229], v[96:99]
	s_setprio 0
	s_setprio 1
	v_mfma_f32_16x16x32_bf16 v[92:95], v[154:157], v[198:201], v[92:95]
	v_mfma_f32_16x16x32_bf16 v[88:91], v[162:165], v[198:201], v[88:91]
	v_mfma_f32_16x16x32_bf16 v[84:87], v[154:157], v[206:209], v[84:87]
	v_mfma_f32_16x16x32_bf16 v[80:83], v[162:165], v[206:209], v[80:83]
	v_mfma_f32_16x16x32_bf16 v[76:79], v[154:157], v[214:217], v[76:79]
	v_mfma_f32_16x16x32_bf16 v[72:75], v[162:165], v[214:217], v[72:75]
	v_mfma_f32_16x16x32_bf16 v[68:71], v[154:157], v[222:225], v[68:71]
	v_mfma_f32_16x16x32_bf16 v[64:67], v[162:165], v[222:225], v[64:67]
	v_mfma_f32_16x16x32_bf16 v[92:95], v[158:161], v[202:205], v[92:95]
	v_mfma_f32_16x16x32_bf16 v[88:91], v[194:197], v[202:205], v[88:91]
	v_mfma_f32_16x16x32_bf16 v[84:87], v[158:161], v[210:213], v[84:87]
	v_mfma_f32_16x16x32_bf16 v[80:83], v[194:197], v[210:213], v[80:83]
	v_mfma_f32_16x16x32_bf16 v[76:79], v[158:161], v[218:221], v[76:79]
	v_mfma_f32_16x16x32_bf16 v[72:75], v[194:197], v[218:221], v[72:75]
	v_mfma_f32_16x16x32_bf16 v[68:71], v[158:161], v[226:229], v[68:71]
	v_mfma_f32_16x16x32_bf16 v[64:67], v[194:197], v[226:229], v[64:67]
	s_setprio 0
	s_barrier
	s_mov_b32 m0, s17
	v_lshl_add_u64 v[166:167], v[166:167], 0, s[34:35]
	ds_read_b128 v[198:201], v137 offset:49152
	ds_read_b128 v[202:205], v137 offset:50176
	ds_read_b128 v[206:209], v137 offset:51200
	ds_read_b128 v[210:213], v137 offset:52224
	ds_read_b128 v[214:217], v137 offset:53248
	ds_read_b128 v[218:221], v137 offset:54272
	ds_read_b128 v[222:225], v137 offset:55296
	ds_read_b128 v[226:229], v137 offset:56320
	v_lshl_add_u64 v[166:167], v[230:231], 0, s[34:35]
	s_mov_b32 m0, s24
	s_nop 0
	v_lshl_add_u64 v[166:167], v[232:233], 0, s[34:35]
	s_mov_b32 m0, s97
	s_nop 0
	v_lshl_add_u64 v[166:167], v[234:235], 0, s[34:35]
	s_mov_b32 m0, vcc_hi
	s_nop 0
	v_lshl_add_u64 v[166:167], v[236:237], 0, s[34:35]
	s_mov_b32 m0, s60
	s_nop 0
	v_lshl_add_u64 v[166:167], v[238:239], 0, s[34:35]
	s_mov_b32 m0, s96
	s_nop 0
	s_waitcnt vmcnt(0)
	s_waitcnt lgkmcnt(0)
	s_barrier
	s_setprio 1
	s_waitcnt lgkmcnt(0)
	v_mfma_f32_16x16x32_bf16 v[60:63], v[138:141], v[198:201], v[60:63]
	v_mfma_f32_16x16x32_bf16 v[56:59], v[146:149], v[198:201], v[56:59]
	v_mfma_f32_16x16x32_bf16 v[52:55], v[138:141], v[206:209], v[52:55]
	v_mfma_f32_16x16x32_bf16 v[48:51], v[146:149], v[206:209], v[48:51]
	v_mfma_f32_16x16x32_bf16 v[44:47], v[138:141], v[214:217], v[44:47]
	v_mfma_f32_16x16x32_bf16 v[40:43], v[146:149], v[214:217], v[40:43]
	v_mfma_f32_16x16x32_bf16 v[36:39], v[138:141], v[222:225], v[36:39]
	v_mfma_f32_16x16x32_bf16 v[32:35], v[146:149], v[222:225], v[32:35]
	v_mfma_f32_16x16x32_bf16 v[60:63], v[142:145], v[202:205], v[60:63]
	v_mfma_f32_16x16x32_bf16 v[56:59], v[150:153], v[202:205], v[56:59]
	v_mfma_f32_16x16x32_bf16 v[52:55], v[142:145], v[210:213], v[52:55]
	v_mfma_f32_16x16x32_bf16 v[48:51], v[150:153], v[210:213], v[48:51]
	v_mfma_f32_16x16x32_bf16 v[44:47], v[142:145], v[218:221], v[44:47]
	v_mfma_f32_16x16x32_bf16 v[40:43], v[150:153], v[218:221], v[40:43]
	v_mfma_f32_16x16x32_bf16 v[36:39], v[142:145], v[226:229], v[36:39]
	v_mfma_f32_16x16x32_bf16 v[32:35], v[150:153], v[226:229], v[32:35]
	s_setprio 0
	s_setprio 1
	v_mfma_f32_16x16x32_bf16 v[28:31], v[154:157], v[198:201], v[28:31]
	v_mfma_f32_16x16x32_bf16 v[24:27], v[162:165], v[198:201], v[24:27]
	v_mfma_f32_16x16x32_bf16 v[20:23], v[154:157], v[206:209], v[20:23]
	v_mfma_f32_16x16x32_bf16 v[16:19], v[162:165], v[206:209], v[16:19]
	v_mfma_f32_16x16x32_bf16 v[12:15], v[154:157], v[214:217], v[12:15]
	v_mfma_f32_16x16x32_bf16 v[8:11], v[162:165], v[214:217], v[8:11]
	v_mfma_f32_16x16x32_bf16 v[4:7], v[154:157], v[222:225], v[4:7]
	v_mfma_f32_16x16x32_bf16 v[0:3], v[162:165], v[222:225], v[0:3]
	v_mfma_f32_16x16x32_bf16 v[28:31], v[158:161], v[202:205], v[28:31]
	v_mfma_f32_16x16x32_bf16 v[24:27], v[194:197], v[202:205], v[24:27]
	v_mfma_f32_16x16x32_bf16 v[20:23], v[158:161], v[210:213], v[20:23]
	v_mfma_f32_16x16x32_bf16 v[16:19], v[194:197], v[210:213], v[16:19]
	v_mfma_f32_16x16x32_bf16 v[12:15], v[158:161], v[218:221], v[12:15]
	v_mfma_f32_16x16x32_bf16 v[8:11], v[194:197], v[218:221], v[8:11]
	v_mfma_f32_16x16x32_bf16 v[4:7], v[158:161], v[226:229], v[4:7]
	v_mfma_f32_16x16x32_bf16 v[0:3], v[194:197], v[226:229], v[0:3]
	s_setprio 0
	s_barrier
	s_cmp_lt_u32 s36, s62
	s_mov_b64 s[26:27], s[48:49]
	s_mov_b32 s14, s36
	s_waitcnt vmcnt(0)
	s_cmpk_gt_u32 s89, 0xff
	s_cbranch_scc1 .LBB0_79
	s_barrier

.LBB0_86:
	ds_read_b128 v[4:7], v3
	v_add_u32_e32 v10, s14, v2
	v_add_u32_e32 v8, 0x80, v10
	v_ashrrev_i32_e32 v9, 31, v8
	s_add_i32 s14, s14, 64
	s_waitcnt lgkmcnt(0)
	v_cvt_pk_bf16_f32 v4, v4, v5
	v_cvt_pk_bf16_f32 v5, v6, v7
	v_lshlrev_b64 v[6:7], 11, v[8:9]
	v_lshl_add_u64 v[6:7], v[0:1], 0, v[6:7]
	global_store_dwordx2 v[6:7], v[4:5], off offset:256
	ds_read_b128 v[4:7], v3 offset:16640
	v_add_u32_e32 v8, 0x90, v10
	v_ashrrev_i32_e32 v9, 31, v8
	s_cmpk_lg_i32 s14, 0x80
	s_waitcnt lgkmcnt(0)
	v_cvt_pk_bf16_f32 v4, v4, v5
	v_cvt_pk_bf16_f32 v5, v6, v7
	v_lshlrev_b64 v[6:7], 11, v[8:9]
	v_lshl_add_u64 v[6:7], v[0:1], 0, v[6:7]
	global_store_dwordx2 v[6:7], v[4:5], off offset:256
	ds_read_b128 v[4:7], v3 offset:33280
	v_add_u32_e32 v8, 0xa0, v10
	v_ashrrev_i32_e32 v9, 31, v8
	s_waitcnt lgkmcnt(0)
	v_cvt_pk_bf16_f32 v4, v4, v5
	v_cvt_pk_bf16_f32 v5, v6, v7
	v_lshlrev_b64 v[6:7], 11, v[8:9]
	v_lshl_add_u64 v[6:7], v[0:1], 0, v[6:7]
	global_store_dwordx2 v[6:7], v[4:5], off offset:256
	ds_read_b128 v[4:7], v3 offset:49920
	v_add_u32_e32 v8, 0xb0, v10
	v_ashrrev_i32_e32 v9, 31, v8
	v_add_u32_e32 v3, 0x10400, v3
	s_waitcnt lgkmcnt(0)
	v_cvt_pk_bf16_f32 v4, v4, v5
	v_cvt_pk_bf16_f32 v5, v6, v7
	v_lshlrev_b64 v[6:7], 11, v[8:9]
	v_lshl_add_u64 v[6:7], v[0:1], 0, v[6:7]
	global_store_dwordx2 v[6:7], v[4:5], off offset:256
	s_cbranch_scc1 .LBB0_86
	s_barrier
	s_branch .LBB0_71
	s_nop 0
	s_nop 0
	s_nop 0
	s_nop 0
	s_nop 0
	s_nop 0
	s_nop 0
	s_nop 0
	s_nop 0
	s_nop 0
	s_nop 0
	s_nop 0

.LBB0_210:
	s_add_u32 s14, s60, s44
	s_addc_u32 s15, s91, s45
	v_or_b32_e32 v138, 0x10000, v136
	v_add_u32_e32 v142, 0x10400, v136
	v_add_u32_e32 v146, 0x10800, v136
	v_add_u32_e32 v150, 0x10c00, v136
	v_or_b32_e32 v154, 0x14000, v136
	v_add_u32_e32 v158, 0x14400, v136
	v_add_u32_e32 v162, 0x14800, v136
	s_add_u32 s14, s14, 0x4000100
	ds_read_b128 v[138:141], v138
	ds_read_b128 v[142:145], v142
	ds_read_b128 v[146:149], v146
	ds_read_b128 v[150:153], v150
	ds_read_b128 v[154:157], v154
	ds_read_b128 v[158:161], v158
	v_add_u32_e32 v166, 0x14c00, v136
	ds_read_b128 v[162:165], v162
	ds_read_b128 v[194:197], v166
	s_addc_u32 s15, s15, 0
	s_add_u32 s36, s92, s44
	s_addc_u32 s37, s93, s45
	s_cmpk_eq_i32 s44, 0x700
	s_cselect_b32 s27, s43, s15
	s_cselect_b32 s26, s42, s14
	s_cselect_b32 s15, s41, s37
	s_cselect_b32 s14, s40, s36
	v_lshl_add_u64 v[166:167], v[130:131], 0, s[44:45]
	s_add_i32 m0, s16, 0xc000
	ds_read_b128 v[198:201], v137
	ds_read_b128 v[202:205], v137 offset:1024
	ds_read_b128 v[206:209], v137 offset:2048
	ds_read_b128 v[210:213], v137 offset:3072
	ds_read_b128 v[214:217], v137 offset:4096
	ds_read_b128 v[218:221], v137 offset:5120
	ds_read_b128 v[222:225], v137 offset:6144
	ds_read_b128 v[226:229], v137 offset:7168
	global_load_lds_dwordx4 v[166:167], off
	v_lshl_add_u64 v[166:167], v[132:133], 0, s[44:45]
	s_add_i32 m0, s16, 0xe000
	s_nop 0
	global_load_lds_dwordx4 v[166:167], off
	s_waitcnt vmcnt(8)
	s_waitcnt lgkmcnt(0)
	s_barrier
	s_setprio 1
	s_waitcnt lgkmcnt(0)
	v_mfma_f32_16x16x32_bf16 v[124:127], v[138:141], v[198:201], v[124:127]
	v_mfma_f32_16x16x32_bf16 v[120:123], v[146:149], v[198:201], v[120:123]
	v_mfma_f32_16x16x32_bf16 v[116:119], v[138:141], v[206:209], v[116:119]
	v_mfma_f32_16x16x32_bf16 v[112:115], v[146:149], v[206:209], v[112:115]
	v_mfma_f32_16x16x32_bf16 v[108:111], v[138:141], v[214:217], v[108:111]
	v_mfma_f32_16x16x32_bf16 v[104:107], v[146:149], v[214:217], v[104:107]
	v_mfma_f32_16x16x32_bf16 v[100:103], v[138:141], v[222:225], v[100:103]
	v_mfma_f32_16x16x32_bf16 v[96:99], v[146:149], v[222:225], v[96:99]
	v_mfma_f32_16x16x32_bf16 v[124:127], v[142:145], v[202:205], v[124:127]
	v_mfma_f32_16x16x32_bf16 v[120:123], v[150:153], v[202:205], v[120:123]
	v_mfma_f32_16x16x32_bf16 v[116:119], v[142:145], v[210:213], v[116:119]
	v_mfma_f32_16x16x32_bf16 v[112:115], v[150:153], v[210:213], v[112:115]
	v_mfma_f32_16x16x32_bf16 v[108:111], v[142:145], v[218:221], v[108:111]
	v_mfma_f32_16x16x32_bf16 v[104:107], v[150:153], v[218:221], v[104:107]
	v_mfma_f32_16x16x32_bf16 v[100:103], v[142:145], v[226:229], v[100:103]
	v_mfma_f32_16x16x32_bf16 v[96:99], v[150:153], v[226:229], v[96:99]
	s_setprio 0
	s_setprio 1
	v_mfma_f32_16x16x32_bf16 v[92:95], v[154:157], v[198:201], v[92:95]
	v_mfma_f32_16x16x32_bf16 v[88:91], v[162:165], v[198:201], v[88:91]
	v_mfma_f32_16x16x32_bf16 v[84:87], v[154:157], v[206:209], v[84:87]
	v_mfma_f32_16x16x32_bf16 v[80:83], v[162:165], v[206:209], v[80:83]
	v_mfma_f32_16x16x32_bf16 v[76:79], v[154:157], v[214:217], v[76:79]
	v_mfma_f32_16x16x32_bf16 v[72:75], v[162:165], v[214:217], v[72:75]
	v_mfma_f32_16x16x32_bf16 v[68:71], v[154:157], v[222:225], v[68:71]
	v_mfma_f32_16x16x32_bf16 v[64:67], v[162:165], v[222:225], v[64:67]
	v_mfma_f32_16x16x32_bf16 v[92:95], v[158:161], v[202:205], v[92:95]
	v_mfma_f32_16x16x32_bf16 v[88:91], v[194:197], v[202:205], v[88:91]
	v_mfma_f32_16x16x32_bf16 v[84:87], v[158:161], v[210:213], v[84:87]
	v_mfma_f32_16x16x32_bf16 v[80:83], v[194:197], v[210:213], v[80:83]
	v_mfma_f32_16x16x32_bf16 v[76:79], v[158:161], v[218:221], v[76:79]
	v_mfma_f32_16x16x32_bf16 v[72:75], v[194:197], v[218:221], v[72:75]
	v_mfma_f32_16x16x32_bf16 v[68:71], v[158:161], v[226:229], v[68:71]
	v_mfma_f32_16x16x32_bf16 v[64:67], v[194:197], v[226:229], v[64:67]
	s_setprio 0
	s_barrier
	s_mov_b32 m0, s17
	v_lshl_add_u64 v[166:167], s[14:15], 0, v[168:169]
	s_add_u32 s36, s14, 0x40000
	ds_read_b128 v[198:201], v137 offset:16384
	ds_read_b128 v[202:205], v137 offset:17408
	ds_read_b128 v[206:209], v137 offset:18432
	ds_read_b128 v[210:213], v137 offset:19456
	ds_read_b128 v[214:217], v137 offset:20480
	ds_read_b128 v[218:221], v137 offset:21504
	ds_read_b128 v[222:225], v137 offset:22528
	ds_read_b128 v[226:229], v137 offset:23552
	global_load_lds_dwordx4 v[166:167], off
	v_lshl_add_u64 v[230:231], s[14:15], 0, v[128:129]
	s_mov_b32 m0, s28
	s_addc_u32 s37, s15, 0
	global_load_lds_dwordx4 v[230:231], off
	v_lshl_add_u64 v[232:233], s[36:37], 0, v[168:169]
	s_mov_b32 m0, s29
	v_lshl_add_u64 v[234:235], s[26:27], 0, v[128:129]
	global_load_lds_dwordx4 v[232:233], off
	v_lshl_add_u64 v[232:233], s[36:37], 0, v[128:129]
	s_mov_b32 m0, s46
	s_nop 0
	global_load_lds_dwordx4 v[232:233], off
	v_lshl_add_u64 v[232:233], s[26:27], 0, v[168:169]
	s_mov_b32 m0, s16
	s_nop 0
	global_load_lds_dwordx4 v[232:233], off
	s_mov_b32 m0, s47
	s_nop 0
	global_load_lds_dwordx4 v[234:235], off
	s_waitcnt vmcnt(8)
	s_waitcnt lgkmcnt(0)
	s_barrier
	s_setprio 1
	s_waitcnt lgkmcnt(0)
	v_mfma_f32_16x16x32_bf16 v[60:63], v[138:141], v[198:201], v[60:63]
	v_mfma_f32_16x16x32_bf16 v[56:59], v[146:149], v[198:201], v[56:59]
	v_mfma_f32_16x16x32_bf16 v[52:55], v[138:141], v[206:209], v[52:55]
	v_mfma_f32_16x16x32_bf16 v[48:51], v[146:149], v[206:209], v[48:51]
	v_mfma_f32_16x16x32_bf16 v[44:47], v[138:141], v[214:217], v[44:47]
	v_mfma_f32_16x16x32_bf16 v[40:43], v[146:149], v[214:217], v[40:43]
	v_mfma_f32_16x16x32_bf16 v[36:39], v[138:141], v[222:225], v[36:39]
	v_mfma_f32_16x16x32_bf16 v[32:35], v[146:149], v[222:225], v[32:35]
	v_mfma_f32_16x16x32_bf16 v[60:63], v[142:145], v[202:205], v[60:63]
	v_mfma_f32_16x16x32_bf16 v[56:59], v[150:153], v[202:205], v[56:59]
	v_mfma_f32_16x16x32_bf16 v[52:55], v[142:145], v[210:213], v[52:55]
	v_mfma_f32_16x16x32_bf16 v[48:51], v[150:153], v[210:213], v[48:51]
	v_mfma_f32_16x16x32_bf16 v[44:47], v[142:145], v[218:221], v[44:47]
	v_mfma_f32_16x16x32_bf16 v[40:43], v[150:153], v[218:221], v[40:43]
	v_mfma_f32_16x16x32_bf16 v[36:39], v[142:145], v[226:229], v[36:39]
	v_mfma_f32_16x16x32_bf16 v[32:35], v[150:153], v[226:229], v[32:35]
	s_setprio 0
	s_setprio 1
	v_mfma_f32_16x16x32_bf16 v[28:31], v[154:157], v[198:201], v[28:31]
	v_mfma_f32_16x16x32_bf16 v[24:27], v[162:165], v[198:201], v[24:27]
	v_mfma_f32_16x16x32_bf16 v[20:23], v[154:157], v[206:209], v[20:23]
	v_mfma_f32_16x16x32_bf16 v[16:19], v[162:165], v[206:209], v[16:19]
	v_mfma_f32_16x16x32_bf16 v[12:15], v[154:157], v[214:217], v[12:15]
	v_mfma_f32_16x16x32_bf16 v[8:11], v[162:165], v[214:217], v[8:11]
	v_mfma_f32_16x16x32_bf16 v[4:7], v[154:157], v[222:225], v[4:7]
	v_mfma_f32_16x16x32_bf16 v[0:3], v[162:165], v[222:225], v[0:3]
	v_mfma_f32_16x16x32_bf16 v[28:31], v[158:161], v[202:205], v[28:31]
	v_mfma_f32_16x16x32_bf16 v[24:27], v[194:197], v[202:205], v[24:27]
	v_mfma_f32_16x16x32_bf16 v[20:23], v[158:161], v[210:213], v[20:23]
	v_mfma_f32_16x16x32_bf16 v[16:19], v[194:197], v[210:213], v[16:19]
	v_mfma_f32_16x16x32_bf16 v[12:15], v[158:161], v[218:221], v[12:15]
	v_mfma_f32_16x16x32_bf16 v[8:11], v[194:197], v[218:221], v[8:11]
	v_mfma_f32_16x16x32_bf16 v[4:7], v[158:161], v[226:229], v[4:7]
	v_mfma_f32_16x16x32_bf16 v[0:3], v[194:197], v[226:229], v[0:3]
	s_setprio 0
	s_barrier
	v_or_b32_e32 v138, 0x18000, v136
	v_add_u32_e32 v142, 0x18400, v136
	v_add_u32_e32 v146, 0x18800, v136
	v_add_u32_e32 v150, 0x18c00, v136
	v_or_b32_e32 v154, 0x1c000, v136
	v_add_u32_e32 v158, 0x1c400, v136
	v_add_u32_e32 v162, 0x1c800, v136
	ds_read_b128 v[138:141], v138
	ds_read_b128 v[142:145], v142
	ds_read_b128 v[146:149], v146
	ds_read_b128 v[150:153], v150
	ds_read_b128 v[154:157], v154
	ds_read_b128 v[158:161], v158
	v_add_u32_e32 v180, 0x1cc00, v136
	ds_read_b128 v[162:165], v162
	ds_read_b128 v[194:197], v180
	s_add_u32 s26, s26, 0x40000
	s_addc_u32 s27, s27, 0
	s_mov_b32 m0, s49
	v_lshl_add_u64 v[236:237], s[26:27], 0, v[168:169]
	ds_read_b128 v[198:201], v137 offset:32768
	ds_read_b128 v[202:205], v137 offset:33792
	ds_read_b128 v[206:209], v137 offset:34816
	ds_read_b128 v[210:213], v137 offset:35840
	ds_read_b128 v[214:217], v137 offset:36864
	ds_read_b128 v[218:221], v137 offset:37888
	ds_read_b128 v[222:225], v137 offset:38912
	ds_read_b128 v[226:229], v137 offset:39936
	global_load_lds_dwordx4 v[236:237], off
	v_lshl_add_u64 v[236:237], s[26:27], 0, v[128:129]
	s_mov_b32 m0, s54
	s_nop 0
	global_load_lds_dwordx4 v[236:237], off
	s_waitcnt vmcnt(8)
	s_waitcnt lgkmcnt(0)
	s_barrier
	s_setprio 1
	s_waitcnt lgkmcnt(0)
	v_mfma_f32_16x16x32_bf16 v[124:127], v[138:141], v[198:201], v[124:127]
	v_mfma_f32_16x16x32_bf16 v[120:123], v[146:149], v[198:201], v[120:123]
	v_mfma_f32_16x16x32_bf16 v[116:119], v[138:141], v[206:209], v[116:119]
	v_mfma_f32_16x16x32_bf16 v[112:115], v[146:149], v[206:209], v[112:115]
	v_mfma_f32_16x16x32_bf16 v[108:111], v[138:141], v[214:217], v[108:111]
	v_mfma_f32_16x16x32_bf16 v[104:107], v[146:149], v[214:217], v[104:107]
	v_mfma_f32_16x16x32_bf16 v[100:103], v[138:141], v[222:225], v[100:103]
	v_mfma_f32_16x16x32_bf16 v[96:99], v[146:149], v[222:225], v[96:99]
	v_mfma_f32_16x16x32_bf16 v[124:127], v[142:145], v[202:205], v[124:127]
	v_mfma_f32_16x16x32_bf16 v[120:123], v[150:153], v[202:205], v[120:123]
	v_mfma_f32_16x16x32_bf16 v[116:119], v[142:145], v[210:213], v[116:119]
	v_mfma_f32_16x16x32_bf16 v[112:115], v[150:153], v[210:213], v[112:115]
	v_mfma_f32_16x16x32_bf16 v[108:111], v[142:145], v[218:221], v[108:111]
	v_mfma_f32_16x16x32_bf16 v[104:107], v[150:153], v[218:221], v[104:107]
	v_mfma_f32_16x16x32_bf16 v[100:103], v[142:145], v[226:229], v[100:103]
	v_mfma_f32_16x16x32_bf16 v[96:99], v[150:153], v[226:229], v[96:99]
	s_setprio 0
	s_setprio 1
	v_mfma_f32_16x16x32_bf16 v[92:95], v[154:157], v[198:201], v[92:95]
	v_mfma_f32_16x16x32_bf16 v[88:91], v[162:165], v[198:201], v[88:91]
	v_mfma_f32_16x16x32_bf16 v[84:87], v[154:157], v[206:209], v[84:87]
	v_mfma_f32_16x16x32_bf16 v[80:83], v[162:165], v[206:209], v[80:83]
	v_mfma_f32_16x16x32_bf16 v[76:79], v[154:157], v[214:217], v[76:79]
	v_mfma_f32_16x16x32_bf16 v[72:75], v[162:165], v[214:217], v[72:75]
	v_mfma_f32_16x16x32_bf16 v[68:71], v[154:157], v[222:225], v[68:71]
	v_mfma_f32_16x16x32_bf16 v[64:67], v[162:165], v[222:225], v[64:67]
	v_mfma_f32_16x16x32_bf16 v[92:95], v[158:161], v[202:205], v[92:95]
	v_mfma_f32_16x16x32_bf16 v[88:91], v[194:197], v[202:205], v[88:91]
	v_mfma_f32_16x16x32_bf16 v[84:87], v[158:161], v[210:213], v[84:87]
	v_mfma_f32_16x16x32_bf16 v[80:83], v[194:197], v[210:213], v[80:83]
	v_mfma_f32_16x16x32_bf16 v[76:79], v[158:161], v[218:221], v[76:79]
	v_mfma_f32_16x16x32_bf16 v[72:75], v[194:197], v[218:221], v[72:75]
	v_mfma_f32_16x16x32_bf16 v[68:71], v[158:161], v[226:229], v[68:71]
	v_mfma_f32_16x16x32_bf16 v[64:67], v[194:197], v[226:229], v[64:67]
	s_setprio 0
	s_barrier
	s_mov_b32 m0, s56
	v_lshl_add_u64 v[166:167], v[166:167], 0, s[34:35]
	s_add_u32 s14, s14, 0x40080
	ds_read_b128 v[198:201], v137 offset:49152
	ds_read_b128 v[202:205], v137 offset:50176
	ds_read_b128 v[206:209], v137 offset:51200
	ds_read_b128 v[210:213], v137 offset:52224
	ds_read_b128 v[214:217], v137 offset:53248
	ds_read_b128 v[218:221], v137 offset:54272
	ds_read_b128 v[222:225], v137 offset:55296
	ds_read_b128 v[226:229], v137 offset:56320
	global_load_lds_dwordx4 v[166:167], off
	v_lshl_add_u64 v[166:167], v[230:231], 0, s[34:35]
	s_mov_b32 m0, s85
	s_addc_u32 s15, s15, 0
	global_load_lds_dwordx4 v[166:167], off
	v_lshl_add_u64 v[166:167], s[14:15], 0, v[168:169]
	s_mov_b32 m0, s90
	s_nop 0
	global_load_lds_dwordx4 v[166:167], off
	v_lshl_add_u64 v[166:167], s[14:15], 0, v[128:129]
	s_mov_b32 m0, s24
	s_nop 0
	global_load_lds_dwordx4 v[166:167], off
	v_lshl_add_u64 v[166:167], v[232:233], 0, s[34:35]
	s_mov_b32 m0, s86
	s_nop 0
	global_load_lds_dwordx4 v[166:167], off
	v_lshl_add_u64 v[166:167], v[234:235], 0, s[34:35]
	s_mov_b32 m0, s87
	s_nop 0
	global_load_lds_dwordx4 v[166:167], off
	s_waitcnt vmcnt(8)
	s_waitcnt lgkmcnt(0)
	s_barrier
	s_setprio 1
	s_waitcnt lgkmcnt(0)
	v_mfma_f32_16x16x32_bf16 v[60:63], v[138:141], v[198:201], v[60:63]
	v_mfma_f32_16x16x32_bf16 v[56:59], v[146:149], v[198:201], v[56:59]
	v_mfma_f32_16x16x32_bf16 v[52:55], v[138:141], v[206:209], v[52:55]
	v_mfma_f32_16x16x32_bf16 v[48:51], v[146:149], v[206:209], v[48:51]
	v_mfma_f32_16x16x32_bf16 v[44:47], v[138:141], v[214:217], v[44:47]
	v_mfma_f32_16x16x32_bf16 v[40:43], v[146:149], v[214:217], v[40:43]
	v_mfma_f32_16x16x32_bf16 v[36:39], v[138:141], v[222:225], v[36:39]
	v_mfma_f32_16x16x32_bf16 v[32:35], v[146:149], v[222:225], v[32:35]
	v_mfma_f32_16x16x32_bf16 v[60:63], v[142:145], v[202:205], v[60:63]
	v_mfma_f32_16x16x32_bf16 v[56:59], v[150:153], v[202:205], v[56:59]
	v_mfma_f32_16x16x32_bf16 v[52:55], v[142:145], v[210:213], v[52:55]
	v_mfma_f32_16x16x32_bf16 v[48:51], v[150:153], v[210:213], v[48:51]
	v_mfma_f32_16x16x32_bf16 v[44:47], v[142:145], v[218:221], v[44:47]
	v_mfma_f32_16x16x32_bf16 v[40:43], v[150:153], v[218:221], v[40:43]
	v_mfma_f32_16x16x32_bf16 v[36:39], v[142:145], v[226:229], v[36:39]
	v_mfma_f32_16x16x32_bf16 v[32:35], v[150:153], v[226:229], v[32:35]
	s_setprio 0
	s_setprio 1
	v_mfma_f32_16x16x32_bf16 v[28:31], v[154:157], v[198:201], v[28:31]
	v_mfma_f32_16x16x32_bf16 v[24:27], v[162:165], v[198:201], v[24:27]
	v_mfma_f32_16x16x32_bf16 v[20:23], v[154:157], v[206:209], v[20:23]
	v_mfma_f32_16x16x32_bf16 v[16:19], v[162:165], v[206:209], v[16:19]
	v_mfma_f32_16x16x32_bf16 v[12:15], v[154:157], v[214:217], v[12:15]
	v_mfma_f32_16x16x32_bf16 v[8:11], v[162:165], v[214:217], v[8:11]
	v_mfma_f32_16x16x32_bf16 v[4:7], v[154:157], v[222:225], v[4:7]
	v_mfma_f32_16x16x32_bf16 v[0:3], v[162:165], v[222:225], v[0:3]
	v_mfma_f32_16x16x32_bf16 v[28:31], v[158:161], v[202:205], v[28:31]
	v_mfma_f32_16x16x32_bf16 v[24:27], v[194:197], v[202:205], v[24:27]
	v_mfma_f32_16x16x32_bf16 v[20:23], v[158:161], v[210:213], v[20:23]
	v_mfma_f32_16x16x32_bf16 v[16:19], v[194:197], v[210:213], v[16:19]
	v_mfma_f32_16x16x32_bf16 v[12:15], v[158:161], v[218:221], v[12:15]
	v_mfma_f32_16x16x32_bf16 v[8:11], v[194:197], v[218:221], v[8:11]
	v_mfma_f32_16x16x32_bf16 v[4:7], v[158:161], v[226:229], v[4:7]
	v_mfma_f32_16x16x32_bf16 v[0:3], v[194:197], v[226:229], v[0:3]
	s_setprio 0
	s_barrier
	s_add_i32 s94, s94, 2
	s_add_u32 s44, s44, 0x100
	s_addc_u32 s45, s45, 0
	s_cmp_lt_u32 s94, 12
	s_cbranch_scc1 .LBB0_210
	s_add_u32 s14, s60, s44
	s_addc_u32 s15, s91, s45
	v_or_b32_e32 v138, 0x10000, v136
	v_add_u32_e32 v142, 0x10400, v136
	v_add_u32_e32 v146, 0x10800, v136
	v_add_u32_e32 v150, 0x10c00, v136
	v_or_b32_e32 v154, 0x14000, v136
	v_add_u32_e32 v158, 0x14400, v136
	v_add_u32_e32 v162, 0x14800, v136
	s_add_u32 s14, s14, 0x4000100
	ds_read_b128 v[138:141], v138
	ds_read_b128 v[142:145], v142
	ds_read_b128 v[146:149], v146
	ds_read_b128 v[150:153], v150
	ds_read_b128 v[154:157], v154
	ds_read_b128 v[158:161], v158
	v_add_u32_e32 v166, 0x14c00, v136
	ds_read_b128 v[162:165], v162
	ds_read_b128 v[194:197], v166
	s_addc_u32 s15, s15, 0
	s_add_u32 s36, s92, s44
	s_addc_u32 s37, s93, s45
	s_cmpk_eq_i32 s44, 0x700
	s_cselect_b32 s27, s43, s15
	s_cselect_b32 s26, s42, s14
	s_cselect_b32 s15, s41, s37
	s_cselect_b32 s14, s40, s36
	v_lshl_add_u64 v[166:167], v[130:131], 0, s[44:45]
	s_add_i32 m0, s16, 0xc000
	ds_read_b128 v[198:201], v137
	ds_read_b128 v[202:205], v137 offset:1024
	ds_read_b128 v[206:209], v137 offset:2048
	ds_read_b128 v[210:213], v137 offset:3072
	ds_read_b128 v[214:217], v137 offset:4096
	ds_read_b128 v[218:221], v137 offset:5120
	ds_read_b128 v[222:225], v137 offset:6144
	ds_read_b128 v[226:229], v137 offset:7168
	global_load_lds_dwordx4 v[166:167], off
	v_lshl_add_u64 v[166:167], v[132:133], 0, s[44:45]
	s_add_i32 m0, s16, 0xe000
	s_nop 0
	global_load_lds_dwordx4 v[166:167], off
	s_waitcnt vmcnt(8)
	s_waitcnt lgkmcnt(0)
	s_barrier
	s_setprio 1
	s_waitcnt lgkmcnt(0)
	v_mfma_f32_16x16x32_bf16 v[124:127], v[138:141], v[198:201], v[124:127]
	v_mfma_f32_16x16x32_bf16 v[120:123], v[146:149], v[198:201], v[120:123]
	v_mfma_f32_16x16x32_bf16 v[116:119], v[138:141], v[206:209], v[116:119]
	v_mfma_f32_16x16x32_bf16 v[112:115], v[146:149], v[206:209], v[112:115]
	v_mfma_f32_16x16x32_bf16 v[108:111], v[138:141], v[214:217], v[108:111]
	v_mfma_f32_16x16x32_bf16 v[104:107], v[146:149], v[214:217], v[104:107]
	v_mfma_f32_16x16x32_bf16 v[100:103], v[138:141], v[222:225], v[100:103]
	v_mfma_f32_16x16x32_bf16 v[96:99], v[146:149], v[222:225], v[96:99]
	v_mfma_f32_16x16x32_bf16 v[124:127], v[142:145], v[202:205], v[124:127]
	v_mfma_f32_16x16x32_bf16 v[120:123], v[150:153], v[202:205], v[120:123]
	v_mfma_f32_16x16x32_bf16 v[116:119], v[142:145], v[210:213], v[116:119]
	v_mfma_f32_16x16x32_bf16 v[112:115], v[150:153], v[210:213], v[112:115]
	v_mfma_f32_16x16x32_bf16 v[108:111], v[142:145], v[218:221], v[108:111]
	v_mfma_f32_16x16x32_bf16 v[104:107], v[150:153], v[218:221], v[104:107]
	v_mfma_f32_16x16x32_bf16 v[100:103], v[142:145], v[226:229], v[100:103]
	v_mfma_f32_16x16x32_bf16 v[96:99], v[150:153], v[226:229], v[96:99]
	s_setprio 0
	s_setprio 1
	v_mfma_f32_16x16x32_bf16 v[92:95], v[154:157], v[198:201], v[92:95]
	v_mfma_f32_16x16x32_bf16 v[88:91], v[162:165], v[198:201], v[88:91]
	v_mfma_f32_16x16x32_bf16 v[84:87], v[154:157], v[206:209], v[84:87]
	v_mfma_f32_16x16x32_bf16 v[80:83], v[162:165], v[206:209], v[80:83]
	v_mfma_f32_16x16x32_bf16 v[76:79], v[154:157], v[214:217], v[76:79]
	v_mfma_f32_16x16x32_bf16 v[72:75], v[162:165], v[214:217], v[72:75]
	v_mfma_f32_16x16x32_bf16 v[68:71], v[154:157], v[222:225], v[68:71]
	v_mfma_f32_16x16x32_bf16 v[64:67], v[162:165], v[222:225], v[64:67]
	v_mfma_f32_16x16x32_bf16 v[92:95], v[158:161], v[202:205], v[92:95]
	v_mfma_f32_16x16x32_bf16 v[88:91], v[194:197], v[202:205], v[88:91]
	v_mfma_f32_16x16x32_bf16 v[84:87], v[158:161], v[210:213], v[84:87]
	v_mfma_f32_16x16x32_bf16 v[80:83], v[194:197], v[210:213], v[80:83]
	v_mfma_f32_16x16x32_bf16 v[76:79], v[158:161], v[218:221], v[76:79]
	v_mfma_f32_16x16x32_bf16 v[72:75], v[194:197], v[218:221], v[72:75]
	v_mfma_f32_16x16x32_bf16 v[68:71], v[158:161], v[226:229], v[68:71]
	v_mfma_f32_16x16x32_bf16 v[64:67], v[194:197], v[226:229], v[64:67]
	s_setprio 0
	s_barrier
	s_mov_b32 m0, s17
	v_lshl_add_u64 v[166:167], s[14:15], 0, v[168:169]
	s_add_u32 s36, s14, 0x40000
	ds_read_b128 v[198:201], v137 offset:16384
	ds_read_b128 v[202:205], v137 offset:17408
	ds_read_b128 v[206:209], v137 offset:18432
	ds_read_b128 v[210:213], v137 offset:19456
	ds_read_b128 v[214:217], v137 offset:20480
	ds_read_b128 v[218:221], v137 offset:21504
	ds_read_b128 v[222:225], v137 offset:22528
	ds_read_b128 v[226:229], v137 offset:23552
	v_lshl_add_u64 v[230:231], s[14:15], 0, v[128:129]
	s_mov_b32 m0, s28
	s_addc_u32 s37, s15, 0
	v_lshl_add_u64 v[232:233], s[36:37], 0, v[168:169]
	s_mov_b32 m0, s29
	v_lshl_add_u64 v[234:235], s[26:27], 0, v[128:129]
	v_lshl_add_u64 v[232:233], s[36:37], 0, v[128:129]
	s_mov_b32 m0, s46
	s_nop 0
	v_lshl_add_u64 v[232:233], s[26:27], 0, v[168:169]
	s_mov_b32 m0, s16
	s_nop 0
	s_mov_b32 m0, s47
	s_nop 0
	s_waitcnt vmcnt(2)
	s_waitcnt lgkmcnt(0)
	s_barrier
	s_setprio 1
	s_waitcnt lgkmcnt(0)
	v_mfma_f32_16x16x32_bf16 v[60:63], v[138:141], v[198:201], v[60:63]
	v_mfma_f32_16x16x32_bf16 v[56:59], v[146:149], v[198:201], v[56:59]
	v_mfma_f32_16x16x32_bf16 v[52:55], v[138:141], v[206:209], v[52:55]
	v_mfma_f32_16x16x32_bf16 v[48:51], v[146:149], v[206:209], v[48:51]
	v_mfma_f32_16x16x32_bf16 v[44:47], v[138:141], v[214:217], v[44:47]
	v_mfma_f32_16x16x32_bf16 v[40:43], v[146:149], v[214:217], v[40:43]
	v_mfma_f32_16x16x32_bf16 v[36:39], v[138:141], v[222:225], v[36:39]
	v_mfma_f32_16x16x32_bf16 v[32:35], v[146:149], v[222:225], v[32:35]
	v_mfma_f32_16x16x32_bf16 v[60:63], v[142:145], v[202:205], v[60:63]
	v_mfma_f32_16x16x32_bf16 v[56:59], v[150:153], v[202:205], v[56:59]
	v_mfma_f32_16x16x32_bf16 v[52:55], v[142:145], v[210:213], v[52:55]
	v_mfma_f32_16x16x32_bf16 v[48:51], v[150:153], v[210:213], v[48:51]
	v_mfma_f32_16x16x32_bf16 v[44:47], v[142:145], v[218:221], v[44:47]
	v_mfma_f32_16x16x32_bf16 v[40:43], v[150:153], v[218:221], v[40:43]
	v_mfma_f32_16x16x32_bf16 v[36:39], v[142:145], v[226:229], v[36:39]
	v_mfma_f32_16x16x32_bf16 v[32:35], v[150:153], v[226:229], v[32:35]
	s_setprio 0
	s_setprio 1
	v_mfma_f32_16x16x32_bf16 v[28:31], v[154:157], v[198:201], v[28:31]
	v_mfma_f32_16x16x32_bf16 v[24:27], v[162:165], v[198:201], v[24:27]
	v_mfma_f32_16x16x32_bf16 v[20:23], v[154:157], v[206:209], v[20:23]
	v_mfma_f32_16x16x32_bf16 v[16:19], v[162:165], v[206:209], v[16:19]
	v_mfma_f32_16x16x32_bf16 v[12:15], v[154:157], v[214:217], v[12:15]
	v_mfma_f32_16x16x32_bf16 v[8:11], v[162:165], v[214:217], v[8:11]
	v_mfma_f32_16x16x32_bf16 v[4:7], v[154:157], v[222:225], v[4:7]
	v_mfma_f32_16x16x32_bf16 v[0:3], v[162:165], v[222:225], v[0:3]
	v_mfma_f32_16x16x32_bf16 v[28:31], v[158:161], v[202:205], v[28:31]
	v_mfma_f32_16x16x32_bf16 v[24:27], v[194:197], v[202:205], v[24:27]
	v_mfma_f32_16x16x32_bf16 v[20:23], v[158:161], v[210:213], v[20:23]
	v_mfma_f32_16x16x32_bf16 v[16:19], v[194:197], v[210:213], v[16:19]
	v_mfma_f32_16x16x32_bf16 v[12:15], v[158:161], v[218:221], v[12:15]
	v_mfma_f32_16x16x32_bf16 v[8:11], v[194:197], v[218:221], v[8:11]
	v_mfma_f32_16x16x32_bf16 v[4:7], v[158:161], v[226:229], v[4:7]
	v_mfma_f32_16x16x32_bf16 v[0:3], v[194:197], v[226:229], v[0:3]
	s_setprio 0
	s_barrier
	v_or_b32_e32 v138, 0x18000, v136
	v_add_u32_e32 v142, 0x18400, v136
	v_add_u32_e32 v146, 0x18800, v136
	v_add_u32_e32 v150, 0x18c00, v136
	v_or_b32_e32 v154, 0x1c000, v136
	v_add_u32_e32 v158, 0x1c400, v136
	v_add_u32_e32 v162, 0x1c800, v136
	ds_read_b128 v[138:141], v138
	ds_read_b128 v[142:145], v142
	ds_read_b128 v[146:149], v146
	ds_read_b128 v[150:153], v150
	ds_read_b128 v[154:157], v154
	ds_read_b128 v[158:161], v158
	v_add_u32_e32 v180, 0x1cc00, v136
	ds_read_b128 v[162:165], v162
	ds_read_b128 v[194:197], v180
	s_add_u32 s26, s26, 0x40000
	s_addc_u32 s27, s27, 0
	s_mov_b32 m0, s49
	v_lshl_add_u64 v[236:237], s[26:27], 0, v[168:169]
	ds_read_b128 v[198:201], v137 offset:32768
	ds_read_b128 v[202:205], v137 offset:33792
	ds_read_b128 v[206:209], v137 offset:34816
	ds_read_b128 v[210:213], v137 offset:35840
	ds_read_b128 v[214:217], v137 offset:36864
	ds_read_b128 v[218:221], v137 offset:37888
	ds_read_b128 v[222:225], v137 offset:38912
	ds_read_b128 v[226:229], v137 offset:39936
	v_lshl_add_u64 v[236:237], s[26:27], 0, v[128:129]
	s_mov_b32 m0, s54
	s_nop 0
	s_waitcnt vmcnt(0)
	s_waitcnt lgkmcnt(0)
	s_barrier
	s_setprio 1
	s_waitcnt lgkmcnt(0)
	v_mfma_f32_16x16x32_bf16 v[124:127], v[138:141], v[198:201], v[124:127]
	v_mfma_f32_16x16x32_bf16 v[120:123], v[146:149], v[198:201], v[120:123]
	v_mfma_f32_16x16x32_bf16 v[116:119], v[138:141], v[206:209], v[116:119]
	v_mfma_f32_16x16x32_bf16 v[112:115], v[146:149], v[206:209], v[112:115]
	v_mfma_f32_16x16x32_bf16 v[108:111], v[138:141], v[214:217], v[108:111]
	v_mfma_f32_16x16x32_bf16 v[104:107], v[146:149], v[214:217], v[104:107]
	v_mfma_f32_16x16x32_bf16 v[100:103], v[138:141], v[222:225], v[100:103]
	v_mfma_f32_16x16x32_bf16 v[96:99], v[146:149], v[222:225], v[96:99]
	v_mfma_f32_16x16x32_bf16 v[124:127], v[142:145], v[202:205], v[124:127]
	v_mfma_f32_16x16x32_bf16 v[120:123], v[150:153], v[202:205], v[120:123]
	v_mfma_f32_16x16x32_bf16 v[116:119], v[142:145], v[210:213], v[116:119]
	v_mfma_f32_16x16x32_bf16 v[112:115], v[150:153], v[210:213], v[112:115]
	v_mfma_f32_16x16x32_bf16 v[108:111], v[142:145], v[218:221], v[108:111]
	v_mfma_f32_16x16x32_bf16 v[104:107], v[150:153], v[218:221], v[104:107]
	v_mfma_f32_16x16x32_bf16 v[100:103], v[142:145], v[226:229], v[100:103]
	v_mfma_f32_16x16x32_bf16 v[96:99], v[150:153], v[226:229], v[96:99]
	s_setprio 0
	s_setprio 1
	v_mfma_f32_16x16x32_bf16 v[92:95], v[154:157], v[198:201], v[92:95]
	v_mfma_f32_16x16x32_bf16 v[88:91], v[162:165], v[198:201], v[88:91]
	v_mfma_f32_16x16x32_bf16 v[84:87], v[154:157], v[206:209], v[84:87]
	v_mfma_f32_16x16x32_bf16 v[80:83], v[162:165], v[206:209], v[80:83]
	v_mfma_f32_16x16x32_bf16 v[76:79], v[154:157], v[214:217], v[76:79]
	v_mfma_f32_16x16x32_bf16 v[72:75], v[162:165], v[214:217], v[72:75]
	v_mfma_f32_16x16x32_bf16 v[68:71], v[154:157], v[222:225], v[68:71]
	v_mfma_f32_16x16x32_bf16 v[64:67], v[162:165], v[222:225], v[64:67]
	v_mfma_f32_16x16x32_bf16 v[92:95], v[158:161], v[202:205], v[92:95]
	v_mfma_f32_16x16x32_bf16 v[88:91], v[194:197], v[202:205], v[88:91]
	v_mfma_f32_16x16x32_bf16 v[84:87], v[158:161], v[210:213], v[84:87]
	v_mfma_f32_16x16x32_bf16 v[80:83], v[194:197], v[210:213], v[80:83]
	v_mfma_f32_16x16x32_bf16 v[76:79], v[158:161], v[218:221], v[76:79]
	v_mfma_f32_16x16x32_bf16 v[72:75], v[194:197], v[218:221], v[72:75]
	v_mfma_f32_16x16x32_bf16 v[68:71], v[158:161], v[226:229], v[68:71]
	v_mfma_f32_16x16x32_bf16 v[64:67], v[194:197], v[226:229], v[64:67]
	s_setprio 0
	s_barrier
	s_mov_b32 m0, s56
	v_lshl_add_u64 v[166:167], v[166:167], 0, s[34:35]
	s_add_u32 s14, s14, 0x40080
	ds_read_b128 v[198:201], v137 offset:49152
	ds_read_b128 v[202:205], v137 offset:50176
	ds_read_b128 v[206:209], v137 offset:51200
	ds_read_b128 v[210:213], v137 offset:52224
	ds_read_b128 v[214:217], v137 offset:53248
	ds_read_b128 v[218:221], v137 offset:54272
	ds_read_b128 v[222:225], v137 offset:55296
	ds_read_b128 v[226:229], v137 offset:56320
	v_lshl_add_u64 v[166:167], v[230:231], 0, s[34:35]
	s_mov_b32 m0, s85
	s_addc_u32 s15, s15, 0
	v_lshl_add_u64 v[166:167], s[14:15], 0, v[168:169]
	s_mov_b32 m0, s90
	s_nop 0
	v_lshl_add_u64 v[166:167], s[14:15], 0, v[128:129]
	s_mov_b32 m0, s24
	s_nop 0
	v_lshl_add_u64 v[166:167], v[232:233], 0, s[34:35]
	s_mov_b32 m0, s86
	s_nop 0
	v_lshl_add_u64 v[166:167], v[234:235], 0, s[34:35]
	s_mov_b32 m0, s87
	s_nop 0
	s_waitcnt vmcnt(0)
	s_waitcnt lgkmcnt(0)
	s_barrier
	s_setprio 1
	s_waitcnt lgkmcnt(0)
	v_mfma_f32_16x16x32_bf16 v[60:63], v[138:141], v[198:201], v[60:63]
	v_mfma_f32_16x16x32_bf16 v[56:59], v[146:149], v[198:201], v[56:59]
	v_mfma_f32_16x16x32_bf16 v[52:55], v[138:141], v[206:209], v[52:55]
	v_mfma_f32_16x16x32_bf16 v[48:51], v[146:149], v[206:209], v[48:51]
	v_mfma_f32_16x16x32_bf16 v[44:47], v[138:141], v[214:217], v[44:47]
	v_mfma_f32_16x16x32_bf16 v[40:43], v[146:149], v[214:217], v[40:43]
	v_mfma_f32_16x16x32_bf16 v[36:39], v[138:141], v[222:225], v[36:39]
	v_mfma_f32_16x16x32_bf16 v[32:35], v[146:149], v[222:225], v[32:35]
	v_mfma_f32_16x16x32_bf16 v[60:63], v[142:145], v[202:205], v[60:63]
	v_mfma_f32_16x16x32_bf16 v[56:59], v[150:153], v[202:205], v[56:59]
	v_mfma_f32_16x16x32_bf16 v[52:55], v[142:145], v[210:213], v[52:55]
	v_mfma_f32_16x16x32_bf16 v[48:51], v[150:153], v[210:213], v[48:51]
	v_mfma_f32_16x16x32_bf16 v[44:47], v[142:145], v[218:221], v[44:47]
	v_mfma_f32_16x16x32_bf16 v[40:43], v[150:153], v[218:221], v[40:43]
	v_mfma_f32_16x16x32_bf16 v[36:39], v[142:145], v[226:229], v[36:39]
	v_mfma_f32_16x16x32_bf16 v[32:35], v[150:153], v[226:229], v[32:35]
	s_setprio 0
	s_setprio 1
	v_mfma_f32_16x16x32_bf16 v[28:31], v[154:157], v[198:201], v[28:31]
	v_mfma_f32_16x16x32_bf16 v[24:27], v[162:165], v[198:201], v[24:27]
	v_mfma_f32_16x16x32_bf16 v[20:23], v[154:157], v[206:209], v[20:23]
	v_mfma_f32_16x16x32_bf16 v[16:19], v[162:165], v[206:209], v[16:19]
	v_mfma_f32_16x16x32_bf16 v[12:15], v[154:157], v[214:217], v[12:15]
	v_mfma_f32_16x16x32_bf16 v[8:11], v[162:165], v[214:217], v[8:11]
	v_mfma_f32_16x16x32_bf16 v[4:7], v[154:157], v[222:225], v[4:7]
	v_mfma_f32_16x16x32_bf16 v[0:3], v[162:165], v[222:225], v[0:3]
	v_mfma_f32_16x16x32_bf16 v[28:31], v[158:161], v[202:205], v[28:31]
	v_mfma_f32_16x16x32_bf16 v[24:27], v[194:197], v[202:205], v[24:27]
	v_mfma_f32_16x16x32_bf16 v[20:23], v[158:161], v[210:213], v[20:23]
	v_mfma_f32_16x16x32_bf16 v[16:19], v[194:197], v[210:213], v[16:19]
	v_mfma_f32_16x16x32_bf16 v[12:15], v[158:161], v[218:221], v[12:15]
	v_mfma_f32_16x16x32_bf16 v[8:11], v[194:197], v[218:221], v[8:11]
	v_mfma_f32_16x16x32_bf16 v[4:7], v[158:161], v[226:229], v[4:7]
	v_mfma_f32_16x16x32_bf16 v[0:3], v[194:197], v[226:229], v[0:3]
	s_setprio 0
	s_barrier
	s_add_i32 s94, s94, 2
	s_add_u32 s44, s44, 0x100
	s_addc_u32 s45, s45, 0
	s_cmp_lt_u32 s94, 14
	s_waitcnt vmcnt(0)
	s_cmpk_gt_u32 s5, 0xff
	s_cbranch_scc1 .LBB0_213
	s_barrier

.LBB0_446:
	v_readlane_b32 s26, v255, 2
	s_mov_b32 s5, 0
	s_mov_b64 s[90:91], 0x100
	s_mov_b64 s[14:15], 0
	v_readlane_b32 s27, v255, 3
	s_andn2_b64 vcc, exec, s[16:17]
	s_mov_b32 s84, 1.0
	s_cbranch_vccz .LBB0_334
	s_branch .LBB0_335
	s_nop 0
	s_nop 0
	s_nop 0
